# v20 + GEMM phases: first K-iteration of each unit peeled with SrcC=0, accumulator zeroing removed (5 phases)
# baseline (speedup 1.0000x reference)
.LBB0_236:
	s_ashr_i32 s59, s58, 31
	s_xor_b64 s[70:71], s[6:7], -1
	s_lshl_b64 s[28:29], s[58:59], 20
	s_add_u32 s68, s62, s28
	s_addc_u32 s69, s63, s29
	s_and_b64 s[28:29], s[6:7], exec
	s_cselect_b32 s9, s69, s77
	s_cselect_b32 s59, s68, s76
	s_ashr_i32 s61, s60, 31
	s_lshl_b64 s[28:29], s[60:61], 20
	s_add_u32 s72, s64, s28
	s_addc_u32 s73, s65, s29
	s_and_b64 s[28:29], s[6:7], exec
	s_cselect_b32 s61, s73, s79
	s_cselect_b32 s75, s72, s78
	s_bitcmp0_b32 s23, 0
	s_cselect_b64 vcc, -1, 0
	s_add_u32 s76, s76, 0x80080
	s_addc_u32 s77, s77, 0
	s_add_u32 s83, s78, 0x100
	s_addc_u32 s28, s79, 0
	s_mov_b32 s29, -2
	v_cndmask_b32_e32 v173, v164, v163, vcc
	v_cndmask_b32_e32 v174, v166, v165, vcc
	ds_read_b128 v[156:159], v170
	ds_read_b128 v[176:179], v170 offset:1024
	ds_read_b128 v[180:183], v170 offset:2048
	ds_read_b128 v[184:187], v170 offset:3072
	s_add_u32 s33, s76, 0xfff80080
	s_addc_u32 s80, s77, -1
	s_cmp_eq_u32 s29, 28
	s_cselect_b64 vcc, -1, 0
	s_and_b64 s[78:79], vcc, exec
	s_cselect_b32 s81, s9, s80
	s_cselect_b32 s80, s59, s33
	s_cselect_b32 s79, s61, s28
	s_cselect_b32 s78, s75, s83
	s_and_b64 vcc, s[6:7], vcc
	v_cndmask_b32_e32 v132, v153, v173, vcc
	v_lshl_add_u64 v[154:155], s[76:77], 0, v[136:137]
	s_add_i32 m0, s86, 0xc000
	ds_read_b128 v[188:191], v171
	ds_read_b128 v[192:195], v171 offset:1024
	ds_read_b128 v[196:199], v171 offset:2048
	ds_read_b128 v[200:203], v171 offset:3072
	ds_read_b128 v[204:207], v171 offset:4096
	ds_read_b128 v[208:211], v171 offset:5120
	ds_read_b128 v[214:217], v171 offset:6144
	ds_read_b128 v[218:221], v171 offset:7168
	global_load_lds_dwordx4 v[154:155], off
	v_lshl_add_u64 v[154:155], s[76:77], 0, v[138:139]
	s_add_i32 m0, s86, 0xe000
	s_nop 0
	global_load_lds_dwordx4 v[154:155], off
	s_waitcnt lgkmcnt(8)
	s_barrier
	s_waitcnt lgkmcnt(0)
	v_cndmask_b32_e32 v154, v152, v174, vcc
	s_setprio 1
	s_waitcnt lgkmcnt(0)
	v_mfma_f32_16x16x32_bf16 v[124:127], v[156:159], v[188:191], 0
	v_mfma_f32_16x16x32_bf16 v[120:123], v[180:183], v[188:191], 0
	v_mfma_f32_16x16x32_bf16 v[116:119], v[156:159], v[196:199], 0
	v_mfma_f32_16x16x32_bf16 v[112:115], v[180:183], v[196:199], 0
	v_mfma_f32_16x16x32_bf16 v[108:111], v[156:159], v[204:207], 0
	v_mfma_f32_16x16x32_bf16 v[104:107], v[180:183], v[204:207], 0
	v_mfma_f32_16x16x32_bf16 v[100:103], v[156:159], v[214:217], 0
	v_mfma_f32_16x16x32_bf16 v[96:99], v[180:183], v[214:217], 0
	v_mfma_f32_16x16x32_bf16 v[124:127], v[176:179], v[192:195], v[124:127]
	v_mfma_f32_16x16x32_bf16 v[120:123], v[184:187], v[192:195], v[120:123]
	v_mfma_f32_16x16x32_bf16 v[116:119], v[176:179], v[200:203], v[116:119]
	v_mfma_f32_16x16x32_bf16 v[112:115], v[184:187], v[200:203], v[112:115]
	v_mfma_f32_16x16x32_bf16 v[108:111], v[176:179], v[208:211], v[108:111]
	v_mfma_f32_16x16x32_bf16 v[104:107], v[184:187], v[208:211], v[104:107]
	v_mfma_f32_16x16x32_bf16 v[100:103], v[176:179], v[218:221], v[100:103]
	v_mfma_f32_16x16x32_bf16 v[96:99], v[184:187], v[218:221], v[96:99]
	s_setprio 0
	s_barrier
	s_add_i32 s33, s96, s85
	s_mov_b32 m0, s33
	ds_read_b128 v[222:225], v172
	ds_read_b128 v[228:231], v172 offset:1024
	ds_read_b128 v[232:235], v172 offset:2048
	ds_read_b128 v[236:239], v172 offset:3072
	global_load_lds_dwordx4 v132, s[78:79]
	s_add_i32 m0, s33, 0x2000
	v_mov_b32_e32 v155, v133
	global_load_lds_dwordx4 v154, s[78:79]
	s_barrier
	s_waitcnt lgkmcnt(0)
	v_lshl_add_u64 v[160:161], s[78:79], 0, v[132:133]
	v_lshl_add_u64 v[240:241], s[78:79], 0, v[154:155]
	s_setprio 1
	s_waitcnt lgkmcnt(0)
	v_mfma_f32_16x16x32_bf16 v[60:63], v[222:225], v[188:191], 0
	v_mfma_f32_16x16x32_bf16 v[56:59], v[232:235], v[188:191], 0
	v_mfma_f32_16x16x32_bf16 v[52:55], v[222:225], v[196:199], 0
	v_mfma_f32_16x16x32_bf16 v[48:51], v[232:235], v[196:199], 0
	v_mfma_f32_16x16x32_bf16 v[44:47], v[222:225], v[204:207], 0
	v_mfma_f32_16x16x32_bf16 v[40:43], v[232:235], v[204:207], 0
	v_mfma_f32_16x16x32_bf16 v[36:39], v[222:225], v[214:217], 0
	v_mfma_f32_16x16x32_bf16 v[32:35], v[232:235], v[214:217], 0
	v_mfma_f32_16x16x32_bf16 v[60:63], v[228:231], v[192:195], v[60:63]
	v_mfma_f32_16x16x32_bf16 v[56:59], v[236:239], v[192:195], v[56:59]
	v_mfma_f32_16x16x32_bf16 v[52:55], v[228:231], v[200:203], v[52:55]
	v_mfma_f32_16x16x32_bf16 v[48:51], v[236:239], v[200:203], v[48:51]
	v_mfma_f32_16x16x32_bf16 v[44:47], v[228:231], v[208:211], v[44:47]
	v_mfma_f32_16x16x32_bf16 v[40:43], v[236:239], v[208:211], v[40:43]
	v_mfma_f32_16x16x32_bf16 v[36:39], v[228:231], v[218:221], v[36:39]
	v_mfma_f32_16x16x32_bf16 v[32:35], v[236:239], v[218:221], v[32:35]
	s_setprio 0
	s_mov_b32 m0, s86
	v_lshl_add_u64 v[242:243], s[80:81], 0, v[128:129]
	s_barrier
	ds_read_b128 v[188:191], v171 offset:16384
	ds_read_b128 v[192:195], v171 offset:17408
	ds_read_b128 v[196:199], v171 offset:18432
	ds_read_b128 v[200:203], v171 offset:19456
	ds_read_b128 v[204:207], v171 offset:20480
	ds_read_b128 v[208:211], v171 offset:21504
	ds_read_b128 v[214:217], v171 offset:22528
	ds_read_b128 v[218:221], v171 offset:23552
	global_load_lds_dwordx4 v[242:243], off
	v_lshl_add_u64 v[244:245], s[80:81], 0, v[130:131]
	s_mov_b32 m0, s87
	s_nop 0
	global_load_lds_dwordx4 v[244:245], off
	s_barrier
	s_waitcnt lgkmcnt(0)
	s_setprio 1
	s_waitcnt lgkmcnt(0)
	v_mfma_f32_16x16x32_bf16 v[92:95], v[156:159], v[188:191], 0
	v_mfma_f32_16x16x32_bf16 v[88:91], v[180:183], v[188:191], 0
	v_mfma_f32_16x16x32_bf16 v[84:87], v[156:159], v[196:199], 0
	v_mfma_f32_16x16x32_bf16 v[80:83], v[180:183], v[196:199], 0
	v_mfma_f32_16x16x32_bf16 v[76:79], v[156:159], v[204:207], 0
	v_mfma_f32_16x16x32_bf16 v[72:75], v[180:183], v[204:207], 0
	v_mfma_f32_16x16x32_bf16 v[68:71], v[156:159], v[214:217], 0
	v_mfma_f32_16x16x32_bf16 v[64:67], v[180:183], v[214:217], 0
	v_mfma_f32_16x16x32_bf16 v[92:95], v[176:179], v[192:195], v[92:95]
	v_mfma_f32_16x16x32_bf16 v[88:91], v[184:187], v[192:195], v[88:91]
	v_mfma_f32_16x16x32_bf16 v[84:87], v[176:179], v[200:203], v[84:87]
	v_mfma_f32_16x16x32_bf16 v[80:83], v[184:187], v[200:203], v[80:83]
	v_mfma_f32_16x16x32_bf16 v[76:79], v[176:179], v[208:211], v[76:79]
	v_mfma_f32_16x16x32_bf16 v[72:75], v[184:187], v[208:211], v[72:75]
	v_mfma_f32_16x16x32_bf16 v[68:71], v[176:179], v[218:221], v[68:71]
	v_mfma_f32_16x16x32_bf16 v[64:67], v[184:187], v[218:221], v[64:67]
	s_setprio 0
	s_barrier
	s_add_u32 vcc_lo, s78, 0x80000
	s_addc_u32 vcc_hi, s79, 0
	s_add_i32 s33, s97, s85
	s_mov_b32 m0, s33
	s_nop 0
	global_load_lds_dwordx4 v132, vcc
	s_add_i32 m0, s33, 0x2000
	s_nop 0
	global_load_lds_dwordx4 v154, vcc
	s_waitcnt vmcnt(6)
	s_barrier
	s_setprio 1
	v_mfma_f32_16x16x32_bf16 v[28:31], v[222:225], v[188:191], 0
	v_mfma_f32_16x16x32_bf16 v[24:27], v[232:235], v[188:191], 0
	v_mfma_f32_16x16x32_bf16 v[20:23], v[222:225], v[196:199], 0
	v_mfma_f32_16x16x32_bf16 v[16:19], v[232:235], v[196:199], 0
	v_mfma_f32_16x16x32_bf16 v[12:15], v[222:225], v[204:207], 0
	v_mfma_f32_16x16x32_bf16 v[8:11], v[232:235], v[204:207], 0
	v_mfma_f32_16x16x32_bf16 v[4:7], v[222:225], v[214:217], 0
	v_mfma_f32_16x16x32_bf16 v[0:3], v[232:235], v[214:217], 0
	v_mfma_f32_16x16x32_bf16 v[28:31], v[228:231], v[192:195], v[28:31]
	v_mfma_f32_16x16x32_bf16 v[24:27], v[236:239], v[192:195], v[24:27]
	v_mfma_f32_16x16x32_bf16 v[20:23], v[228:231], v[200:203], v[20:23]
	v_mfma_f32_16x16x32_bf16 v[16:19], v[236:239], v[200:203], v[16:19]
	v_mfma_f32_16x16x32_bf16 v[12:15], v[228:231], v[208:211], v[12:15]
	v_mfma_f32_16x16x32_bf16 v[8:11], v[236:239], v[208:211], v[8:11]
	v_mfma_f32_16x16x32_bf16 v[4:7], v[228:231], v[218:221], v[4:7]
	v_mfma_f32_16x16x32_bf16 v[0:3], v[236:239], v[218:221], v[0:3]
	s_setprio 0
	s_add_i32 s33, 0, 0x18000
	v_add_u32_e32 v155, s33, v168
	s_barrier
	ds_read_b128 v[156:159], v155
	ds_read_b128 v[176:179], v155 offset:1024
	ds_read_b128 v[180:183], v155 offset:2048
	ds_read_b128 v[184:187], v155 offset:3072
	s_add_u32 s80, s80, 0x80000
	s_addc_u32 s81, s81, 0
	s_mov_b32 m0, s88
	v_lshl_add_u64 v[222:223], s[80:81], 0, v[128:129]
	ds_read_b128 v[188:191], v171 offset:32768
	ds_read_b128 v[192:195], v171 offset:33792
	ds_read_b128 v[196:199], v171 offset:34816
	ds_read_b128 v[200:203], v171 offset:35840
	ds_read_b128 v[204:207], v171 offset:36864
	ds_read_b128 v[208:211], v171 offset:37888
	ds_read_b128 v[214:217], v171 offset:38912
	ds_read_b128 v[218:221], v171 offset:39936
	global_load_lds_dwordx4 v[222:223], off
	v_lshl_add_u64 v[222:223], s[80:81], 0, v[130:131]
	s_mov_b32 m0, s89
	s_nop 0
	global_load_lds_dwordx4 v[222:223], off
	s_waitcnt lgkmcnt(8)
	s_barrier
	s_waitcnt lgkmcnt(0)
	s_setprio 1
	s_waitcnt lgkmcnt(0)
	v_mfma_f32_16x16x32_bf16 v[124:127], v[156:159], v[188:191], v[124:127]
	v_mfma_f32_16x16x32_bf16 v[120:123], v[180:183], v[188:191], v[120:123]
	v_mfma_f32_16x16x32_bf16 v[116:119], v[156:159], v[196:199], v[116:119]
	v_mfma_f32_16x16x32_bf16 v[112:115], v[180:183], v[196:199], v[112:115]
	v_mfma_f32_16x16x32_bf16 v[108:111], v[156:159], v[204:207], v[108:111]
	v_mfma_f32_16x16x32_bf16 v[104:107], v[180:183], v[204:207], v[104:107]
	v_mfma_f32_16x16x32_bf16 v[100:103], v[156:159], v[214:217], v[100:103]
	v_mfma_f32_16x16x32_bf16 v[96:99], v[180:183], v[214:217], v[96:99]
	v_mfma_f32_16x16x32_bf16 v[124:127], v[176:179], v[192:195], v[124:127]
	v_mfma_f32_16x16x32_bf16 v[120:123], v[184:187], v[192:195], v[120:123]
	v_mfma_f32_16x16x32_bf16 v[116:119], v[176:179], v[200:203], v[116:119]
	v_mfma_f32_16x16x32_bf16 v[112:115], v[184:187], v[200:203], v[112:115]
	v_mfma_f32_16x16x32_bf16 v[108:111], v[176:179], v[208:211], v[108:111]
	v_mfma_f32_16x16x32_bf16 v[104:107], v[184:187], v[208:211], v[104:107]
	v_mfma_f32_16x16x32_bf16 v[100:103], v[176:179], v[218:221], v[100:103]
	v_mfma_f32_16x16x32_bf16 v[96:99], v[184:187], v[218:221], v[96:99]
	s_setprio 0
	s_barrier
	s_add_i32 s80, 0, 0x1c000
	s_add_i32 s33, s33, s85
	v_add_u32_e32 v155, s80, v168
	v_lshl_add_u64 v[160:161], v[160:161], 0, s[14:15]
	s_mov_b32 m0, s33
	ds_read_b128 v[222:225], v155
	ds_read_b128 v[228:231], v155 offset:1024
	ds_read_b128 v[232:235], v155 offset:2048
	ds_read_b128 v[236:239], v155 offset:3072
	global_load_lds_dwordx4 v[160:161], off
	v_lshl_add_u64 v[160:161], v[240:241], 0, s[14:15]
	s_add_i32 m0, s33, 0x2000
	s_nop 0
	global_load_lds_dwordx4 v[160:161], off
	s_barrier
	s_waitcnt lgkmcnt(0)
	s_setprio 1
	s_waitcnt lgkmcnt(0)
	v_mfma_f32_16x16x32_bf16 v[60:63], v[222:225], v[188:191], v[60:63]
	v_mfma_f32_16x16x32_bf16 v[56:59], v[232:235], v[188:191], v[56:59]
	v_mfma_f32_16x16x32_bf16 v[52:55], v[222:225], v[196:199], v[52:55]
	v_mfma_f32_16x16x32_bf16 v[48:51], v[232:235], v[196:199], v[48:51]
	v_mfma_f32_16x16x32_bf16 v[44:47], v[222:225], v[204:207], v[44:47]
	v_mfma_f32_16x16x32_bf16 v[40:43], v[232:235], v[204:207], v[40:43]
	v_mfma_f32_16x16x32_bf16 v[36:39], v[222:225], v[214:217], v[36:39]
	v_mfma_f32_16x16x32_bf16 v[32:35], v[232:235], v[214:217], v[32:35]
	v_mfma_f32_16x16x32_bf16 v[60:63], v[228:231], v[192:195], v[60:63]
	v_mfma_f32_16x16x32_bf16 v[56:59], v[236:239], v[192:195], v[56:59]
	v_mfma_f32_16x16x32_bf16 v[52:55], v[228:231], v[200:203], v[52:55]
	v_mfma_f32_16x16x32_bf16 v[48:51], v[236:239], v[200:203], v[48:51]
	v_mfma_f32_16x16x32_bf16 v[44:47], v[228:231], v[208:211], v[44:47]
	v_mfma_f32_16x16x32_bf16 v[40:43], v[236:239], v[208:211], v[40:43]
	v_mfma_f32_16x16x32_bf16 v[36:39], v[228:231], v[218:221], v[36:39]
	v_mfma_f32_16x16x32_bf16 v[32:35], v[236:239], v[218:221], v[32:35]
	s_setprio 0
	s_mov_b32 m0, s91
	v_lshl_add_u64 v[160:161], v[242:243], 0, s[14:15]
	s_barrier
	ds_read_b128 v[188:191], v171 offset:49152
	ds_read_b128 v[192:195], v171 offset:50176
	ds_read_b128 v[196:199], v171 offset:51200
	ds_read_b128 v[200:203], v171 offset:52224
	ds_read_b128 v[204:207], v171 offset:53248
	ds_read_b128 v[208:211], v171 offset:54272
	ds_read_b128 v[214:217], v171 offset:55296
	ds_read_b128 v[218:221], v171 offset:56320
	global_load_lds_dwordx4 v[160:161], off
	v_lshl_add_u64 v[160:161], v[244:245], 0, s[14:15]
	s_mov_b32 m0, s92
	s_nop 0
	global_load_lds_dwordx4 v[160:161], off
	s_barrier
	s_waitcnt lgkmcnt(0)
	s_setprio 1
	s_waitcnt lgkmcnt(0)
	v_mfma_f32_16x16x32_bf16 v[92:95], v[156:159], v[188:191], v[92:95]
	v_mfma_f32_16x16x32_bf16 v[88:91], v[180:183], v[188:191], v[88:91]
	v_mfma_f32_16x16x32_bf16 v[84:87], v[156:159], v[196:199], v[84:87]
	v_mfma_f32_16x16x32_bf16 v[80:83], v[180:183], v[196:199], v[80:83]
	v_mfma_f32_16x16x32_bf16 v[76:79], v[156:159], v[204:207], v[76:79]
	v_mfma_f32_16x16x32_bf16 v[72:75], v[180:183], v[204:207], v[72:75]
	v_mfma_f32_16x16x32_bf16 v[68:71], v[156:159], v[214:217], v[68:71]
	v_mfma_f32_16x16x32_bf16 v[64:67], v[180:183], v[214:217], v[64:67]
	v_mfma_f32_16x16x32_bf16 v[92:95], v[176:179], v[192:195], v[92:95]
	v_mfma_f32_16x16x32_bf16 v[88:91], v[184:187], v[192:195], v[88:91]
	v_mfma_f32_16x16x32_bf16 v[84:87], v[176:179], v[200:203], v[84:87]
	v_mfma_f32_16x16x32_bf16 v[80:83], v[184:187], v[200:203], v[80:83]
	v_mfma_f32_16x16x32_bf16 v[76:79], v[176:179], v[208:211], v[76:79]
	v_mfma_f32_16x16x32_bf16 v[72:75], v[184:187], v[208:211], v[72:75]
	v_mfma_f32_16x16x32_bf16 v[68:71], v[176:179], v[218:221], v[68:71]
	v_mfma_f32_16x16x32_bf16 v[64:67], v[184:187], v[218:221], v[64:67]
	s_setprio 0
	s_barrier
	s_add_u32 s78, s78, 0x80080
	s_addc_u32 s79, s79, 0
	s_add_i32 s33, s80, s85
	s_mov_b32 m0, s33
	s_nop 0
	global_load_lds_dwordx4 v132, s[78:79]
	s_add_i32 m0, s33, 0x2000
	s_nop 0
	global_load_lds_dwordx4 v154, s[78:79]
	s_waitcnt vmcnt(6)
	s_barrier
	s_setprio 1
	v_mfma_f32_16x16x32_bf16 v[28:31], v[222:225], v[188:191], v[28:31]
	v_mfma_f32_16x16x32_bf16 v[24:27], v[232:235], v[188:191], v[24:27]
	v_mfma_f32_16x16x32_bf16 v[20:23], v[222:225], v[196:199], v[20:23]
	v_mfma_f32_16x16x32_bf16 v[16:19], v[232:235], v[196:199], v[16:19]
	v_mfma_f32_16x16x32_bf16 v[12:15], v[222:225], v[204:207], v[12:15]
	v_mfma_f32_16x16x32_bf16 v[8:11], v[232:235], v[204:207], v[8:11]
	v_mfma_f32_16x16x32_bf16 v[4:7], v[222:225], v[214:217], v[4:7]
	v_mfma_f32_16x16x32_bf16 v[0:3], v[232:235], v[214:217], v[0:3]
	v_mfma_f32_16x16x32_bf16 v[28:31], v[228:231], v[192:195], v[28:31]
	v_mfma_f32_16x16x32_bf16 v[24:27], v[236:239], v[192:195], v[24:27]
	v_mfma_f32_16x16x32_bf16 v[20:23], v[228:231], v[200:203], v[20:23]
	v_mfma_f32_16x16x32_bf16 v[16:19], v[236:239], v[200:203], v[16:19]
	v_mfma_f32_16x16x32_bf16 v[12:15], v[228:231], v[208:211], v[12:15]
	v_mfma_f32_16x16x32_bf16 v[8:11], v[236:239], v[208:211], v[8:11]
	v_mfma_f32_16x16x32_bf16 v[4:7], v[228:231], v[218:221], v[4:7]
	v_mfma_f32_16x16x32_bf16 v[0:3], v[236:239], v[218:221], v[0:3]
	s_setprio 0
	s_add_i32 s29, s29, 2
	s_add_u32 s76, s76, 0x100
	s_addc_u32 s77, s77, 0
	s_add_u32 s83, s83, 0x100
	s_addc_u32 s28, s28, 0
	s_cmp_gt_u32 s29, 29
	s_barrier

.LBB0_693:
	s_ashr_i32 s27, s26, 31
	v_cmp_lt_i64_e32 vcc, s[28:29], v[140:141]
	s_lshl_b64 s[28:29], s[26:27], 20
	s_add_u32 s28, s52, s28
	s_addc_u32 s29, s53, s29
	s_and_b64 s[30:31], vcc, exec
	s_cselect_b32 s27, s29, s35
	s_cselect_b32 s73, s28, s34
	s_ashr_i32 s25, s24, 31
	s_lshl_b64 s[30:31], s[24:25], 20
	s_add_u32 s30, s54, s30
	s_addc_u32 s31, s55, s31
	s_and_b64 s[38:39], vcc, exec
	s_cselect_b32 s25, s31, s37
	s_cselect_b32 s74, s30, s36
	s_add_u32 s34, s34, 0x80080
	s_addc_u32 s35, s35, 0
	s_add_u32 s75, s36, 0x100
	s_addc_u32 s76, s37, 0
	s_mov_b32 s77, -2
	ds_read_b128 v[150:153], v147
	ds_read_b128 v[154:157], v147 offset:1024
	ds_read_b128 v[158:161], v147 offset:2048
	ds_read_b128 v[162:165], v147 offset:3072
	s_add_u32 s33, s34, 0xfff80080
	s_addc_u32 s36, s35, -1
	s_cmp_eq_u32 s77, 28
	s_cselect_b32 s39, s27, s36
	s_cselect_b32 s38, s73, s33
	s_cselect_b32 s37, s25, s76
	s_cselect_b32 s36, s74, s75
	v_lshl_add_u64 v[198:199], s[34:35], 0, v[136:137]
	s_add_i32 m0, s23, 0xc000
	ds_read_b128 v[166:169], v148
	ds_read_b128 v[170:173], v148 offset:1024
	ds_read_b128 v[174:177], v148 offset:2048
	ds_read_b128 v[178:181], v148 offset:3072
	ds_read_b128 v[182:185], v148 offset:4096
	ds_read_b128 v[186:189], v148 offset:5120
	ds_read_b128 v[190:193], v148 offset:6144
	ds_read_b128 v[194:197], v148 offset:7168
	global_load_lds_dwordx4 v[198:199], off
	v_lshl_add_u64 v[198:199], s[34:35], 0, v[138:139]
	s_add_i32 m0, s23, 0xe000
	s_nop 0
	global_load_lds_dwordx4 v[198:199], off
	s_waitcnt lgkmcnt(8)
	s_barrier
	s_waitcnt lgkmcnt(0)
	s_setprio 1
	s_waitcnt lgkmcnt(0)
	v_mfma_f32_16x16x32_bf16 v[124:127], v[150:153], v[166:169], 0
	v_mfma_f32_16x16x32_bf16 v[120:123], v[158:161], v[166:169], 0
	v_mfma_f32_16x16x32_bf16 v[116:119], v[150:153], v[174:177], 0
	v_mfma_f32_16x16x32_bf16 v[112:115], v[158:161], v[174:177], 0
	v_mfma_f32_16x16x32_bf16 v[108:111], v[150:153], v[182:185], 0
	v_mfma_f32_16x16x32_bf16 v[104:107], v[158:161], v[182:185], 0
	v_mfma_f32_16x16x32_bf16 v[100:103], v[150:153], v[190:193], 0
	v_mfma_f32_16x16x32_bf16 v[96:99], v[158:161], v[190:193], 0
	v_mfma_f32_16x16x32_bf16 v[124:127], v[154:157], v[170:173], v[124:127]
	v_mfma_f32_16x16x32_bf16 v[120:123], v[162:165], v[170:173], v[120:123]
	v_mfma_f32_16x16x32_bf16 v[116:119], v[154:157], v[178:181], v[116:119]
	v_mfma_f32_16x16x32_bf16 v[112:115], v[162:165], v[178:181], v[112:115]
	v_mfma_f32_16x16x32_bf16 v[108:111], v[154:157], v[186:189], v[108:111]
	v_mfma_f32_16x16x32_bf16 v[104:107], v[162:165], v[186:189], v[104:107]
	v_mfma_f32_16x16x32_bf16 v[100:103], v[154:157], v[194:197], v[100:103]
	v_mfma_f32_16x16x32_bf16 v[96:99], v[162:165], v[194:197], v[96:99]
	s_setprio 0
	s_barrier
	s_add_i32 s33, s66, s56
	v_lshl_add_u64 v[210:211], s[36:37], 0, v[130:131]
	s_mov_b32 m0, s33
	ds_read_b128 v[198:201], v149
	ds_read_b128 v[202:205], v149 offset:1024
	ds_read_b128 v[206:209], v149 offset:2048
	ds_read_b128 v[216:219], v149 offset:3072
	global_load_lds_dwordx4 v[210:211], off
	v_lshl_add_u64 v[220:221], s[36:37], 0, v[134:135]
	s_add_i32 m0, s33, 0x2000
	s_nop 0
	global_load_lds_dwordx4 v[220:221], off
	s_barrier
	s_waitcnt lgkmcnt(0)
	s_setprio 1
	s_waitcnt lgkmcnt(0)
	v_mfma_f32_16x16x32_bf16 v[80:83], v[198:201], v[166:169], 0
	v_mfma_f32_16x16x32_bf16 v[72:75], v[206:209], v[166:169], 0
	v_mfma_f32_16x16x32_bf16 v[68:71], v[198:201], v[174:177], 0
	v_mfma_f32_16x16x32_bf16 v[60:63], v[206:209], v[174:177], 0
	v_mfma_f32_16x16x32_bf16 v[52:55], v[198:201], v[182:185], 0
	v_mfma_f32_16x16x32_bf16 v[48:51], v[206:209], v[182:185], 0
	v_mfma_f32_16x16x32_bf16 v[36:39], v[198:201], v[190:193], 0
	v_mfma_f32_16x16x32_bf16 v[32:35], v[206:209], v[190:193], 0
	v_mfma_f32_16x16x32_bf16 v[80:83], v[202:205], v[170:173], v[80:83]
	v_mfma_f32_16x16x32_bf16 v[72:75], v[216:219], v[170:173], v[72:75]
	v_mfma_f32_16x16x32_bf16 v[68:71], v[202:205], v[178:181], v[68:71]
	v_mfma_f32_16x16x32_bf16 v[60:63], v[216:219], v[178:181], v[60:63]
	v_mfma_f32_16x16x32_bf16 v[52:55], v[202:205], v[186:189], v[52:55]
	v_mfma_f32_16x16x32_bf16 v[48:51], v[216:219], v[186:189], v[48:51]
	v_mfma_f32_16x16x32_bf16 v[36:39], v[202:205], v[194:197], v[36:39]
	v_mfma_f32_16x16x32_bf16 v[32:35], v[216:219], v[194:197], v[32:35]
	s_setprio 0
	s_mov_b32 m0, s23
	v_lshl_add_u64 v[222:223], s[38:39], 0, v[128:129]
	s_barrier
	ds_read_b128 v[166:169], v148 offset:16384
	ds_read_b128 v[170:173], v148 offset:17408
	ds_read_b128 v[174:177], v148 offset:18432
	ds_read_b128 v[178:181], v148 offset:19456
	ds_read_b128 v[182:185], v148 offset:20480
	ds_read_b128 v[186:189], v148 offset:21504
	ds_read_b128 v[190:193], v148 offset:22528
	ds_read_b128 v[194:197], v148 offset:23552
	global_load_lds_dwordx4 v[222:223], off
	v_lshl_add_u64 v[224:225], s[38:39], 0, v[132:133]
	s_mov_b32 m0, s58
	s_nop 0
	global_load_lds_dwordx4 v[224:225], off
	s_barrier
	s_waitcnt lgkmcnt(0)
	s_setprio 1
	s_waitcnt lgkmcnt(0)
	v_mfma_f32_16x16x32_bf16 v[92:95], v[150:153], v[166:169], 0
	v_mfma_f32_16x16x32_bf16 v[88:91], v[158:161], v[166:169], 0
	v_mfma_f32_16x16x32_bf16 v[84:87], v[150:153], v[174:177], 0
	v_mfma_f32_16x16x32_bf16 v[76:79], v[158:161], v[174:177], 0
	v_mfma_f32_16x16x32_bf16 v[64:67], v[150:153], v[182:185], 0
	v_mfma_f32_16x16x32_bf16 v[56:59], v[158:161], v[182:185], 0
	v_mfma_f32_16x16x32_bf16 v[44:47], v[150:153], v[190:193], 0
	v_mfma_f32_16x16x32_bf16 v[40:43], v[158:161], v[190:193], 0
	v_mfma_f32_16x16x32_bf16 v[92:95], v[154:157], v[170:173], v[92:95]
	v_mfma_f32_16x16x32_bf16 v[88:91], v[162:165], v[170:173], v[88:91]
	v_mfma_f32_16x16x32_bf16 v[84:87], v[154:157], v[178:181], v[84:87]
	v_mfma_f32_16x16x32_bf16 v[76:79], v[162:165], v[178:181], v[76:79]
	v_mfma_f32_16x16x32_bf16 v[64:67], v[154:157], v[186:189], v[64:67]
	v_mfma_f32_16x16x32_bf16 v[56:59], v[162:165], v[186:189], v[56:59]
	v_mfma_f32_16x16x32_bf16 v[44:47], v[154:157], v[194:197], v[44:47]
	v_mfma_f32_16x16x32_bf16 v[40:43], v[162:165], v[194:197], v[40:43]
	s_setprio 0
	s_barrier
	s_add_u32 s78, s36, 0x80000
	s_addc_u32 s79, s37, 0
	s_add_i32 s33, s67, s56
	v_lshl_add_u64 v[150:151], s[78:79], 0, v[130:131]
	s_mov_b32 m0, s33
	s_nop 0
	global_load_lds_dwordx4 v[150:151], off
	v_lshl_add_u64 v[150:151], s[78:79], 0, v[134:135]
	s_add_i32 m0, s33, 0x2000
	s_nop 0
	global_load_lds_dwordx4 v[150:151], off
	s_waitcnt vmcnt(6)
	s_barrier
	s_setprio 1
	v_mfma_f32_16x16x32_bf16 v[28:31], v[198:201], v[166:169], 0
	v_mfma_f32_16x16x32_bf16 v[24:27], v[206:209], v[166:169], 0
	v_mfma_f32_16x16x32_bf16 v[20:23], v[198:201], v[174:177], 0
	v_mfma_f32_16x16x32_bf16 v[16:19], v[206:209], v[174:177], 0
	v_mfma_f32_16x16x32_bf16 v[12:15], v[198:201], v[182:185], 0
	v_mfma_f32_16x16x32_bf16 v[8:11], v[206:209], v[182:185], 0
	v_mfma_f32_16x16x32_bf16 v[4:7], v[198:201], v[190:193], 0
	v_mfma_f32_16x16x32_bf16 v[0:3], v[206:209], v[190:193], 0
	v_mfma_f32_16x16x32_bf16 v[28:31], v[202:205], v[170:173], v[28:31]
	v_mfma_f32_16x16x32_bf16 v[24:27], v[216:219], v[170:173], v[24:27]
	v_mfma_f32_16x16x32_bf16 v[20:23], v[202:205], v[178:181], v[20:23]
	v_mfma_f32_16x16x32_bf16 v[16:19], v[216:219], v[178:181], v[16:19]
	v_mfma_f32_16x16x32_bf16 v[12:15], v[202:205], v[186:189], v[12:15]
	v_mfma_f32_16x16x32_bf16 v[8:11], v[216:219], v[186:189], v[8:11]
	v_mfma_f32_16x16x32_bf16 v[4:7], v[202:205], v[194:197], v[4:7]
	v_mfma_f32_16x16x32_bf16 v[0:3], v[216:219], v[194:197], v[0:3]
	s_setprio 0
	s_add_i32 s33, 0, 0x18000
	v_add_u32_e32 v162, s33, v145
	s_barrier
	ds_read_b128 v[150:153], v162
	ds_read_b128 v[154:157], v162 offset:1024
	ds_read_b128 v[158:161], v162 offset:2048
	ds_read_b128 v[162:165], v162 offset:3072
	s_add_u32 s38, s38, 0x80000
	s_addc_u32 s39, s39, 0
	s_mov_b32 m0, s59
	v_lshl_add_u64 v[198:199], s[38:39], 0, v[128:129]
	ds_read_b128 v[166:169], v148 offset:32768
	ds_read_b128 v[170:173], v148 offset:33792
	ds_read_b128 v[174:177], v148 offset:34816
	ds_read_b128 v[178:181], v148 offset:35840
	ds_read_b128 v[182:185], v148 offset:36864
	ds_read_b128 v[186:189], v148 offset:37888
	ds_read_b128 v[190:193], v148 offset:38912
	ds_read_b128 v[194:197], v148 offset:39936
	global_load_lds_dwordx4 v[198:199], off
	v_lshl_add_u64 v[198:199], s[38:39], 0, v[132:133]
	s_mov_b32 m0, s60
	s_nop 0
	global_load_lds_dwordx4 v[198:199], off
	s_waitcnt lgkmcnt(8)
	s_barrier
	s_waitcnt lgkmcnt(0)
	s_setprio 1
	s_waitcnt lgkmcnt(0)
	v_mfma_f32_16x16x32_bf16 v[124:127], v[150:153], v[166:169], v[124:127]
	v_mfma_f32_16x16x32_bf16 v[120:123], v[158:161], v[166:169], v[120:123]
	v_mfma_f32_16x16x32_bf16 v[116:119], v[150:153], v[174:177], v[116:119]
	v_mfma_f32_16x16x32_bf16 v[112:115], v[158:161], v[174:177], v[112:115]
	v_mfma_f32_16x16x32_bf16 v[108:111], v[150:153], v[182:185], v[108:111]
	v_mfma_f32_16x16x32_bf16 v[104:107], v[158:161], v[182:185], v[104:107]
	v_mfma_f32_16x16x32_bf16 v[100:103], v[150:153], v[190:193], v[100:103]
	v_mfma_f32_16x16x32_bf16 v[96:99], v[158:161], v[190:193], v[96:99]
	v_mfma_f32_16x16x32_bf16 v[124:127], v[154:157], v[170:173], v[124:127]
	v_mfma_f32_16x16x32_bf16 v[120:123], v[162:165], v[170:173], v[120:123]
	v_mfma_f32_16x16x32_bf16 v[116:119], v[154:157], v[178:181], v[116:119]
	v_mfma_f32_16x16x32_bf16 v[112:115], v[162:165], v[178:181], v[112:115]
	v_mfma_f32_16x16x32_bf16 v[108:111], v[154:157], v[186:189], v[108:111]
	v_mfma_f32_16x16x32_bf16 v[104:107], v[162:165], v[186:189], v[104:107]
	v_mfma_f32_16x16x32_bf16 v[100:103], v[154:157], v[194:197], v[100:103]
	v_mfma_f32_16x16x32_bf16 v[96:99], v[162:165], v[194:197], v[96:99]
	s_setprio 0
	s_barrier
	s_add_i32 s38, 0, 0x1c000
	s_add_i32 s33, s33, s56
	v_add_u32_e32 v216, s38, v145
	v_lshl_add_u64 v[210:211], v[210:211], 0, s[14:15]
	s_mov_b32 m0, s33
	ds_read_b128 v[198:201], v216
	ds_read_b128 v[202:205], v216 offset:1024
	ds_read_b128 v[206:209], v216 offset:2048
	ds_read_b128 v[216:219], v216 offset:3072
	global_load_lds_dwordx4 v[210:211], off
	v_lshl_add_u64 v[210:211], v[220:221], 0, s[14:15]
	s_add_i32 m0, s33, 0x2000
	s_nop 0
	global_load_lds_dwordx4 v[210:211], off
	s_barrier
	s_waitcnt lgkmcnt(0)
	s_setprio 1
	s_waitcnt lgkmcnt(0)
	v_mfma_f32_16x16x32_bf16 v[80:83], v[198:201], v[166:169], v[80:83]
	v_mfma_f32_16x16x32_bf16 v[72:75], v[206:209], v[166:169], v[72:75]
	v_mfma_f32_16x16x32_bf16 v[68:71], v[198:201], v[174:177], v[68:71]
	v_mfma_f32_16x16x32_bf16 v[60:63], v[206:209], v[174:177], v[60:63]
	v_mfma_f32_16x16x32_bf16 v[52:55], v[198:201], v[182:185], v[52:55]
	v_mfma_f32_16x16x32_bf16 v[48:51], v[206:209], v[182:185], v[48:51]
	v_mfma_f32_16x16x32_bf16 v[36:39], v[198:201], v[190:193], v[36:39]
	v_mfma_f32_16x16x32_bf16 v[32:35], v[206:209], v[190:193], v[32:35]
	v_mfma_f32_16x16x32_bf16 v[80:83], v[202:205], v[170:173], v[80:83]
	v_mfma_f32_16x16x32_bf16 v[72:75], v[216:219], v[170:173], v[72:75]
	v_mfma_f32_16x16x32_bf16 v[68:71], v[202:205], v[178:181], v[68:71]
	v_mfma_f32_16x16x32_bf16 v[60:63], v[216:219], v[178:181], v[60:63]
	v_mfma_f32_16x16x32_bf16 v[52:55], v[202:205], v[186:189], v[52:55]
	v_mfma_f32_16x16x32_bf16 v[48:51], v[216:219], v[186:189], v[48:51]
	v_mfma_f32_16x16x32_bf16 v[36:39], v[202:205], v[194:197], v[36:39]
	v_mfma_f32_16x16x32_bf16 v[32:35], v[216:219], v[194:197], v[32:35]
	s_setprio 0
	s_mov_b32 m0, s63
	v_lshl_add_u64 v[210:211], v[222:223], 0, s[14:15]
	s_barrier
	ds_read_b128 v[166:169], v148 offset:49152
	ds_read_b128 v[170:173], v148 offset:50176
	ds_read_b128 v[174:177], v148 offset:51200
	ds_read_b128 v[178:181], v148 offset:52224
	ds_read_b128 v[182:185], v148 offset:53248
	ds_read_b128 v[186:189], v148 offset:54272
	ds_read_b128 v[190:193], v148 offset:55296
	ds_read_b128 v[194:197], v148 offset:56320
	global_load_lds_dwordx4 v[210:211], off
	v_lshl_add_u64 v[210:211], v[224:225], 0, s[14:15]
	s_mov_b32 m0, s64
	s_nop 0
	global_load_lds_dwordx4 v[210:211], off
	s_barrier
	s_waitcnt lgkmcnt(0)
	s_setprio 1
	s_waitcnt lgkmcnt(0)
	v_mfma_f32_16x16x32_bf16 v[92:95], v[150:153], v[166:169], v[92:95]
	v_mfma_f32_16x16x32_bf16 v[88:91], v[158:161], v[166:169], v[88:91]
	v_mfma_f32_16x16x32_bf16 v[84:87], v[150:153], v[174:177], v[84:87]
	v_mfma_f32_16x16x32_bf16 v[76:79], v[158:161], v[174:177], v[76:79]
	v_mfma_f32_16x16x32_bf16 v[64:67], v[150:153], v[182:185], v[64:67]
	v_mfma_f32_16x16x32_bf16 v[56:59], v[158:161], v[182:185], v[56:59]
	v_mfma_f32_16x16x32_bf16 v[44:47], v[150:153], v[190:193], v[44:47]
	v_mfma_f32_16x16x32_bf16 v[40:43], v[158:161], v[190:193], v[40:43]
	v_mfma_f32_16x16x32_bf16 v[92:95], v[154:157], v[170:173], v[92:95]
	v_mfma_f32_16x16x32_bf16 v[88:91], v[162:165], v[170:173], v[88:91]
	v_mfma_f32_16x16x32_bf16 v[84:87], v[154:157], v[178:181], v[84:87]
	v_mfma_f32_16x16x32_bf16 v[76:79], v[162:165], v[178:181], v[76:79]
	v_mfma_f32_16x16x32_bf16 v[64:67], v[154:157], v[186:189], v[64:67]
	v_mfma_f32_16x16x32_bf16 v[56:59], v[162:165], v[186:189], v[56:59]
	v_mfma_f32_16x16x32_bf16 v[44:47], v[154:157], v[194:197], v[44:47]
	v_mfma_f32_16x16x32_bf16 v[40:43], v[162:165], v[194:197], v[40:43]
	s_setprio 0
	s_barrier
	s_add_u32 s36, s36, 0x80080
	s_addc_u32 s37, s37, 0
	s_add_i32 s33, s38, s56
	v_lshl_add_u64 v[150:151], s[36:37], 0, v[130:131]
	s_mov_b32 m0, s33
	s_nop 0
	global_load_lds_dwordx4 v[150:151], off
	v_lshl_add_u64 v[150:151], s[36:37], 0, v[134:135]
	s_add_i32 m0, s33, 0x2000
	s_nop 0
	global_load_lds_dwordx4 v[150:151], off
	s_waitcnt vmcnt(6)
	s_barrier
	s_setprio 1
	v_mfma_f32_16x16x32_bf16 v[28:31], v[198:201], v[166:169], v[28:31]
	v_mfma_f32_16x16x32_bf16 v[24:27], v[206:209], v[166:169], v[24:27]
	v_mfma_f32_16x16x32_bf16 v[20:23], v[198:201], v[174:177], v[20:23]
	v_mfma_f32_16x16x32_bf16 v[16:19], v[206:209], v[174:177], v[16:19]
	v_mfma_f32_16x16x32_bf16 v[12:15], v[198:201], v[182:185], v[12:15]
	v_mfma_f32_16x16x32_bf16 v[8:11], v[206:209], v[182:185], v[8:11]
	v_mfma_f32_16x16x32_bf16 v[4:7], v[198:201], v[190:193], v[4:7]
	v_mfma_f32_16x16x32_bf16 v[0:3], v[206:209], v[190:193], v[0:3]
	v_mfma_f32_16x16x32_bf16 v[28:31], v[202:205], v[170:173], v[28:31]
	v_mfma_f32_16x16x32_bf16 v[24:27], v[216:219], v[170:173], v[24:27]
	v_mfma_f32_16x16x32_bf16 v[20:23], v[202:205], v[178:181], v[20:23]
	v_mfma_f32_16x16x32_bf16 v[16:19], v[216:219], v[178:181], v[16:19]
	v_mfma_f32_16x16x32_bf16 v[12:15], v[202:205], v[186:189], v[12:15]
	v_mfma_f32_16x16x32_bf16 v[8:11], v[216:219], v[186:189], v[8:11]
	v_mfma_f32_16x16x32_bf16 v[4:7], v[202:205], v[194:197], v[4:7]
	v_mfma_f32_16x16x32_bf16 v[0:3], v[216:219], v[194:197], v[0:3]
	s_setprio 0
	s_add_i32 s77, s77, 2
	s_add_u32 s34, s34, 0x100
	s_addc_u32 s35, s35, 0
	s_add_u32 s75, s75, 0x100
	s_addc_u32 s76, s76, 0
	s_cmp_gt_u32 s77, 29
	s_barrier

.LBB0_819:
	s_ashr_i32 s19, s18, 31
	v_cmp_lt_i64_e32 vcc, s[20:21], v[140:141]
	s_lshl_b64 s[20:21], s[18:19], 20
	s_add_u32 s20, s35, s20
	s_addc_u32 s21, s36, s21
	s_and_b64 s[22:23], vcc, exec
	s_cselect_b32 s19, s21, s25
	s_cselect_b32 s63, s20, s24
	s_ashr_i32 s15, s14, 31
	s_lshl_b64 s[22:23], s[14:15], 20
	s_add_u32 s22, s31, s22
	s_addc_u32 s23, s34, s23
	s_and_b64 s[28:29], vcc, exec
	s_cselect_b32 s15, s23, s27
	s_cselect_b32 s64, s22, s26
	s_add_u32 s24, s24, 0x80080
	s_addc_u32 s25, s25, 0
	s_add_u32 s65, s26, 0x100
	s_addc_u32 s66, s27, 0
	s_mov_b32 s67, -2
	ds_read_b128 v[152:155], v148
	ds_read_b128 v[156:159], v148 offset:1024
	ds_read_b128 v[160:163], v148 offset:2048
	ds_read_b128 v[164:167], v148 offset:3072
	s_add_u32 s26, s24, 0xfff80080
	s_addc_u32 s27, s25, -1
	s_cmp_eq_u32 s67, 28
	s_cselect_b32 s29, s19, s27
	s_cselect_b32 s28, s63, s26
	s_cselect_b32 s27, s15, s66
	s_cselect_b32 s26, s64, s65
	v_lshl_add_u64 v[196:197], s[24:25], 0, v[136:137]
	s_add_i32 m0, s13, 0xc000
	ds_read_b128 v[168:171], v149
	ds_read_b128 v[172:175], v149 offset:1024
	ds_read_b128 v[176:179], v149 offset:2048
	ds_read_b128 v[180:183], v149 offset:3072
	ds_read_b128 v[184:187], v149 offset:4096
	ds_read_b128 v[188:191], v149 offset:5120
	ds_read_b128 v[192:195], v149 offset:6144
	ds_read_b128 v[200:203], v149 offset:7168
	global_load_lds_dwordx4 v[196:197], off
	v_lshl_add_u64 v[196:197], s[24:25], 0, v[138:139]
	s_add_i32 m0, s13, 0xe000
	s_nop 0
	global_load_lds_dwordx4 v[196:197], off
	s_waitcnt lgkmcnt(8)
	s_barrier
	s_waitcnt lgkmcnt(0)
	s_setprio 1
	s_waitcnt lgkmcnt(0)
	v_mfma_f32_16x16x32_bf16 v[124:127], v[152:155], v[168:171], 0
	v_mfma_f32_16x16x32_bf16 v[120:123], v[160:163], v[168:171], 0
	v_mfma_f32_16x16x32_bf16 v[116:119], v[152:155], v[176:179], 0
	v_mfma_f32_16x16x32_bf16 v[112:115], v[160:163], v[176:179], 0
	v_mfma_f32_16x16x32_bf16 v[108:111], v[152:155], v[184:187], 0
	v_mfma_f32_16x16x32_bf16 v[104:107], v[160:163], v[184:187], 0
	v_mfma_f32_16x16x32_bf16 v[100:103], v[152:155], v[192:195], 0
	v_mfma_f32_16x16x32_bf16 v[96:99], v[160:163], v[192:195], 0
	v_mfma_f32_16x16x32_bf16 v[124:127], v[156:159], v[172:175], v[124:127]
	v_mfma_f32_16x16x32_bf16 v[120:123], v[164:167], v[172:175], v[120:123]
	v_mfma_f32_16x16x32_bf16 v[116:119], v[156:159], v[180:183], v[116:119]
	v_mfma_f32_16x16x32_bf16 v[112:115], v[164:167], v[180:183], v[112:115]
	v_mfma_f32_16x16x32_bf16 v[108:111], v[156:159], v[188:191], v[108:111]
	v_mfma_f32_16x16x32_bf16 v[104:107], v[164:167], v[188:191], v[104:107]
	v_mfma_f32_16x16x32_bf16 v[100:103], v[156:159], v[200:203], v[100:103]
	v_mfma_f32_16x16x32_bf16 v[96:99], v[164:167], v[200:203], v[96:99]
	s_setprio 0
	s_barrier
	s_add_i32 s33, s59, s30
	v_lshl_add_u64 v[196:197], s[26:27], 0, v[130:131]
	s_mov_b32 m0, s33
	ds_read_b128 v[204:207], v150
	ds_read_b128 v[208:211], v150 offset:1024
	ds_read_b128 v[216:219], v150 offset:2048
	ds_read_b128 v[220:223], v150 offset:3072
	global_load_lds_dwordx4 v[196:197], off
	v_lshl_add_u64 v[224:225], s[26:27], 0, v[128:129]
	s_add_i32 m0, s33, 0x2000
	s_nop 0
	global_load_lds_dwordx4 v[224:225], off
	s_barrier
	s_waitcnt lgkmcnt(0)
	s_setprio 1
	s_waitcnt lgkmcnt(0)
	v_mfma_f32_16x16x32_bf16 v[84:87], v[204:207], v[168:171], 0
	v_mfma_f32_16x16x32_bf16 v[76:79], v[216:219], v[168:171], 0
	v_mfma_f32_16x16x32_bf16 v[68:71], v[204:207], v[176:179], 0
	v_mfma_f32_16x16x32_bf16 v[64:67], v[216:219], v[176:179], 0
	v_mfma_f32_16x16x32_bf16 v[52:55], v[204:207], v[184:187], 0
	v_mfma_f32_16x16x32_bf16 v[48:51], v[216:219], v[184:187], 0
	v_mfma_f32_16x16x32_bf16 v[40:43], v[204:207], v[192:195], 0
	v_mfma_f32_16x16x32_bf16 v[32:35], v[216:219], v[192:195], 0
	v_mfma_f32_16x16x32_bf16 v[84:87], v[208:211], v[172:175], v[84:87]
	v_mfma_f32_16x16x32_bf16 v[76:79], v[220:223], v[172:175], v[76:79]
	v_mfma_f32_16x16x32_bf16 v[68:71], v[208:211], v[180:183], v[68:71]
	v_mfma_f32_16x16x32_bf16 v[64:67], v[220:223], v[180:183], v[64:67]
	v_mfma_f32_16x16x32_bf16 v[52:55], v[208:211], v[188:191], v[52:55]
	v_mfma_f32_16x16x32_bf16 v[48:51], v[220:223], v[188:191], v[48:51]
	v_mfma_f32_16x16x32_bf16 v[40:43], v[208:211], v[200:203], v[40:43]
	v_mfma_f32_16x16x32_bf16 v[32:35], v[220:223], v[200:203], v[32:35]
	s_setprio 0
	s_mov_b32 m0, s13
	v_lshl_add_u64 v[230:231], s[28:29], 0, v[134:135]
	s_barrier
	ds_read_b128 v[168:171], v149 offset:16384
	ds_read_b128 v[172:175], v149 offset:17408
	ds_read_b128 v[176:179], v149 offset:18432
	ds_read_b128 v[180:183], v149 offset:19456
	ds_read_b128 v[184:187], v149 offset:20480
	ds_read_b128 v[188:191], v149 offset:21504
	ds_read_b128 v[192:195], v149 offset:22528
	ds_read_b128 v[200:203], v149 offset:23552
	global_load_lds_dwordx4 v[230:231], off
	v_lshl_add_u64 v[232:233], s[28:29], 0, v[132:133]
	s_mov_b32 m0, s39
	s_nop 0
	global_load_lds_dwordx4 v[232:233], off
	s_barrier
	s_waitcnt lgkmcnt(0)
	s_setprio 1
	s_waitcnt lgkmcnt(0)
	v_mfma_f32_16x16x32_bf16 v[92:95], v[152:155], v[168:171], 0
	v_mfma_f32_16x16x32_bf16 v[88:91], v[160:163], v[168:171], 0
	v_mfma_f32_16x16x32_bf16 v[80:83], v[152:155], v[176:179], 0
	v_mfma_f32_16x16x32_bf16 v[72:75], v[160:163], v[176:179], 0
	v_mfma_f32_16x16x32_bf16 v[60:63], v[152:155], v[184:187], 0
	v_mfma_f32_16x16x32_bf16 v[56:59], v[160:163], v[184:187], 0
	v_mfma_f32_16x16x32_bf16 v[44:47], v[152:155], v[192:195], 0
	v_mfma_f32_16x16x32_bf16 v[36:39], v[160:163], v[192:195], 0
	v_mfma_f32_16x16x32_bf16 v[92:95], v[156:159], v[172:175], v[92:95]
	v_mfma_f32_16x16x32_bf16 v[88:91], v[164:167], v[172:175], v[88:91]
	v_mfma_f32_16x16x32_bf16 v[80:83], v[156:159], v[180:183], v[80:83]
	v_mfma_f32_16x16x32_bf16 v[72:75], v[164:167], v[180:183], v[72:75]
	v_mfma_f32_16x16x32_bf16 v[60:63], v[156:159], v[188:191], v[60:63]
	v_mfma_f32_16x16x32_bf16 v[56:59], v[164:167], v[188:191], v[56:59]
	v_mfma_f32_16x16x32_bf16 v[44:47], v[156:159], v[200:203], v[44:47]
	v_mfma_f32_16x16x32_bf16 v[36:39], v[164:167], v[200:203], v[36:39]
	s_setprio 0
	s_barrier
	s_add_u32 s68, s26, 0x80000
	s_addc_u32 s69, s27, 0
	s_add_i32 s33, s60, s30
	v_lshl_add_u64 v[152:153], s[68:69], 0, v[130:131]
	s_mov_b32 m0, s33
	s_nop 0
	global_load_lds_dwordx4 v[152:153], off
	v_lshl_add_u64 v[152:153], s[68:69], 0, v[128:129]
	s_add_i32 m0, s33, 0x2000
	s_nop 0
	global_load_lds_dwordx4 v[152:153], off
	s_waitcnt vmcnt(6)
	s_barrier
	s_setprio 1
	v_mfma_f32_16x16x32_bf16 v[28:31], v[204:207], v[168:171], 0
	v_mfma_f32_16x16x32_bf16 v[24:27], v[216:219], v[168:171], 0
	v_mfma_f32_16x16x32_bf16 v[20:23], v[204:207], v[176:179], 0
	v_mfma_f32_16x16x32_bf16 v[16:19], v[216:219], v[176:179], 0
	v_mfma_f32_16x16x32_bf16 v[12:15], v[204:207], v[184:187], 0
	v_mfma_f32_16x16x32_bf16 v[8:11], v[216:219], v[184:187], 0
	v_mfma_f32_16x16x32_bf16 v[4:7], v[204:207], v[192:195], 0
	v_mfma_f32_16x16x32_bf16 v[0:3], v[216:219], v[192:195], 0
	v_mfma_f32_16x16x32_bf16 v[28:31], v[208:211], v[172:175], v[28:31]
	v_mfma_f32_16x16x32_bf16 v[24:27], v[220:223], v[172:175], v[24:27]
	v_mfma_f32_16x16x32_bf16 v[20:23], v[208:211], v[180:183], v[20:23]
	v_mfma_f32_16x16x32_bf16 v[16:19], v[220:223], v[180:183], v[16:19]
	v_mfma_f32_16x16x32_bf16 v[12:15], v[208:211], v[188:191], v[12:15]
	v_mfma_f32_16x16x32_bf16 v[8:11], v[220:223], v[188:191], v[8:11]
	v_mfma_f32_16x16x32_bf16 v[4:7], v[208:211], v[200:203], v[4:7]
	v_mfma_f32_16x16x32_bf16 v[0:3], v[220:223], v[200:203], v[0:3]
	s_setprio 0
	s_add_i32 s33, 0, 0x18000
	v_add_u32_e32 v151, s33, v146
	s_barrier
	ds_read_b128 v[152:155], v151
	ds_read_b128 v[156:159], v151 offset:1024
	ds_read_b128 v[160:163], v151 offset:2048
	ds_read_b128 v[164:167], v151 offset:3072
	s_add_u32 s28, s28, 0x80000
	s_addc_u32 s29, s29, 0
	s_mov_b32 m0, s52
	v_lshl_add_u64 v[204:205], s[28:29], 0, v[134:135]
	ds_read_b128 v[168:171], v149 offset:32768
	ds_read_b128 v[172:175], v149 offset:33792
	ds_read_b128 v[176:179], v149 offset:34816
	ds_read_b128 v[180:183], v149 offset:35840
	ds_read_b128 v[184:187], v149 offset:36864
	ds_read_b128 v[188:191], v149 offset:37888
	ds_read_b128 v[192:195], v149 offset:38912
	ds_read_b128 v[200:203], v149 offset:39936
	global_load_lds_dwordx4 v[204:205], off
	v_lshl_add_u64 v[204:205], s[28:29], 0, v[132:133]
	s_mov_b32 m0, s53
	s_nop 0
	global_load_lds_dwordx4 v[204:205], off
	s_waitcnt lgkmcnt(8)
	s_barrier
	s_waitcnt lgkmcnt(0)
	s_setprio 1
	s_waitcnt lgkmcnt(0)
	v_mfma_f32_16x16x32_bf16 v[124:127], v[152:155], v[168:171], v[124:127]
	v_mfma_f32_16x16x32_bf16 v[120:123], v[160:163], v[168:171], v[120:123]
	v_mfma_f32_16x16x32_bf16 v[116:119], v[152:155], v[176:179], v[116:119]
	v_mfma_f32_16x16x32_bf16 v[112:115], v[160:163], v[176:179], v[112:115]
	v_mfma_f32_16x16x32_bf16 v[108:111], v[152:155], v[184:187], v[108:111]
	v_mfma_f32_16x16x32_bf16 v[104:107], v[160:163], v[184:187], v[104:107]
	v_mfma_f32_16x16x32_bf16 v[100:103], v[152:155], v[192:195], v[100:103]
	v_mfma_f32_16x16x32_bf16 v[96:99], v[160:163], v[192:195], v[96:99]
	v_mfma_f32_16x16x32_bf16 v[124:127], v[156:159], v[172:175], v[124:127]
	v_mfma_f32_16x16x32_bf16 v[120:123], v[164:167], v[172:175], v[120:123]
	v_mfma_f32_16x16x32_bf16 v[116:119], v[156:159], v[180:183], v[116:119]
	v_mfma_f32_16x16x32_bf16 v[112:115], v[164:167], v[180:183], v[112:115]
	v_mfma_f32_16x16x32_bf16 v[108:111], v[156:159], v[188:191], v[108:111]
	v_mfma_f32_16x16x32_bf16 v[104:107], v[164:167], v[188:191], v[104:107]
	v_mfma_f32_16x16x32_bf16 v[100:103], v[156:159], v[200:203], v[100:103]
	v_mfma_f32_16x16x32_bf16 v[96:99], v[164:167], v[200:203], v[96:99]
	s_setprio 0
	s_barrier
	s_add_i32 s28, 0, 0x1c000
	s_add_i32 s29, s33, s30
	v_add_u32_e32 v151, s28, v146
	v_lshl_add_u64 v[196:197], v[196:197], 0, s[10:11]
	s_mov_b32 m0, s29
	ds_read_b128 v[204:207], v151
	ds_read_b128 v[208:211], v151 offset:1024
	ds_read_b128 v[216:219], v151 offset:2048
	ds_read_b128 v[220:223], v151 offset:3072
	global_load_lds_dwordx4 v[196:197], off
	v_lshl_add_u64 v[196:197], v[224:225], 0, s[10:11]
	s_add_i32 m0, s29, 0x2000
	s_nop 0
	global_load_lds_dwordx4 v[196:197], off
	s_barrier
	s_waitcnt lgkmcnt(0)
	s_setprio 1
	s_waitcnt lgkmcnt(0)
	v_mfma_f32_16x16x32_bf16 v[84:87], v[204:207], v[168:171], v[84:87]
	v_mfma_f32_16x16x32_bf16 v[76:79], v[216:219], v[168:171], v[76:79]
	v_mfma_f32_16x16x32_bf16 v[68:71], v[204:207], v[176:179], v[68:71]
	v_mfma_f32_16x16x32_bf16 v[64:67], v[216:219], v[176:179], v[64:67]
	v_mfma_f32_16x16x32_bf16 v[52:55], v[204:207], v[184:187], v[52:55]
	v_mfma_f32_16x16x32_bf16 v[48:51], v[216:219], v[184:187], v[48:51]
	v_mfma_f32_16x16x32_bf16 v[40:43], v[204:207], v[192:195], v[40:43]
	v_mfma_f32_16x16x32_bf16 v[32:35], v[216:219], v[192:195], v[32:35]
	v_mfma_f32_16x16x32_bf16 v[84:87], v[208:211], v[172:175], v[84:87]
	v_mfma_f32_16x16x32_bf16 v[76:79], v[220:223], v[172:175], v[76:79]
	v_mfma_f32_16x16x32_bf16 v[68:71], v[208:211], v[180:183], v[68:71]
	v_mfma_f32_16x16x32_bf16 v[64:67], v[220:223], v[180:183], v[64:67]
	v_mfma_f32_16x16x32_bf16 v[52:55], v[208:211], v[188:191], v[52:55]
	v_mfma_f32_16x16x32_bf16 v[48:51], v[220:223], v[188:191], v[48:51]
	v_mfma_f32_16x16x32_bf16 v[40:43], v[208:211], v[200:203], v[40:43]
	v_mfma_f32_16x16x32_bf16 v[32:35], v[220:223], v[200:203], v[32:35]
	s_setprio 0
	s_mov_b32 m0, s55
	v_lshl_add_u64 v[196:197], v[230:231], 0, s[10:11]
	s_barrier
	ds_read_b128 v[168:171], v149 offset:49152
	ds_read_b128 v[172:175], v149 offset:50176
	ds_read_b128 v[176:179], v149 offset:51200
	ds_read_b128 v[180:183], v149 offset:52224
	ds_read_b128 v[184:187], v149 offset:53248
	ds_read_b128 v[188:191], v149 offset:54272
	ds_read_b128 v[192:195], v149 offset:55296
	ds_read_b128 v[200:203], v149 offset:56320
	global_load_lds_dwordx4 v[196:197], off
	v_lshl_add_u64 v[196:197], v[232:233], 0, s[10:11]
	s_mov_b32 m0, s56
	s_nop 0
	global_load_lds_dwordx4 v[196:197], off
	s_barrier
	s_waitcnt lgkmcnt(0)
	s_setprio 1
	s_waitcnt lgkmcnt(0)
	v_mfma_f32_16x16x32_bf16 v[92:95], v[152:155], v[168:171], v[92:95]
	v_mfma_f32_16x16x32_bf16 v[88:91], v[160:163], v[168:171], v[88:91]
	v_mfma_f32_16x16x32_bf16 v[80:83], v[152:155], v[176:179], v[80:83]
	v_mfma_f32_16x16x32_bf16 v[72:75], v[160:163], v[176:179], v[72:75]
	v_mfma_f32_16x16x32_bf16 v[60:63], v[152:155], v[184:187], v[60:63]
	v_mfma_f32_16x16x32_bf16 v[56:59], v[160:163], v[184:187], v[56:59]
	v_mfma_f32_16x16x32_bf16 v[44:47], v[152:155], v[192:195], v[44:47]
	v_mfma_f32_16x16x32_bf16 v[36:39], v[160:163], v[192:195], v[36:39]
	v_mfma_f32_16x16x32_bf16 v[92:95], v[156:159], v[172:175], v[92:95]
	v_mfma_f32_16x16x32_bf16 v[88:91], v[164:167], v[172:175], v[88:91]
	v_mfma_f32_16x16x32_bf16 v[80:83], v[156:159], v[180:183], v[80:83]
	v_mfma_f32_16x16x32_bf16 v[72:75], v[164:167], v[180:183], v[72:75]
	v_mfma_f32_16x16x32_bf16 v[60:63], v[156:159], v[188:191], v[60:63]
	v_mfma_f32_16x16x32_bf16 v[56:59], v[164:167], v[188:191], v[56:59]
	v_mfma_f32_16x16x32_bf16 v[44:47], v[156:159], v[200:203], v[44:47]
	v_mfma_f32_16x16x32_bf16 v[36:39], v[164:167], v[200:203], v[36:39]
	s_setprio 0
	s_barrier
	s_add_u32 s26, s26, 0x80080
	s_addc_u32 s27, s27, 0
	s_add_i32 s28, s28, s30
	v_lshl_add_u64 v[152:153], s[26:27], 0, v[130:131]
	s_mov_b32 m0, s28
	s_nop 0
	global_load_lds_dwordx4 v[152:153], off
	v_lshl_add_u64 v[152:153], s[26:27], 0, v[128:129]
	s_add_i32 m0, s28, 0x2000
	s_nop 0
	global_load_lds_dwordx4 v[152:153], off
	s_waitcnt vmcnt(6)
	s_barrier
	s_setprio 1
	v_mfma_f32_16x16x32_bf16 v[28:31], v[204:207], v[168:171], v[28:31]
	v_mfma_f32_16x16x32_bf16 v[24:27], v[216:219], v[168:171], v[24:27]
	v_mfma_f32_16x16x32_bf16 v[20:23], v[204:207], v[176:179], v[20:23]
	v_mfma_f32_16x16x32_bf16 v[16:19], v[216:219], v[176:179], v[16:19]
	v_mfma_f32_16x16x32_bf16 v[12:15], v[204:207], v[184:187], v[12:15]
	v_mfma_f32_16x16x32_bf16 v[8:11], v[216:219], v[184:187], v[8:11]
	v_mfma_f32_16x16x32_bf16 v[4:7], v[204:207], v[192:195], v[4:7]
	v_mfma_f32_16x16x32_bf16 v[0:3], v[216:219], v[192:195], v[0:3]
	v_mfma_f32_16x16x32_bf16 v[28:31], v[208:211], v[172:175], v[28:31]
	v_mfma_f32_16x16x32_bf16 v[24:27], v[220:223], v[172:175], v[24:27]
	v_mfma_f32_16x16x32_bf16 v[20:23], v[208:211], v[180:183], v[20:23]
	v_mfma_f32_16x16x32_bf16 v[16:19], v[220:223], v[180:183], v[16:19]
	v_mfma_f32_16x16x32_bf16 v[12:15], v[208:211], v[188:191], v[12:15]
	v_mfma_f32_16x16x32_bf16 v[8:11], v[220:223], v[188:191], v[8:11]
	v_mfma_f32_16x16x32_bf16 v[4:7], v[208:211], v[200:203], v[4:7]
	v_mfma_f32_16x16x32_bf16 v[0:3], v[220:223], v[200:203], v[0:3]
	s_setprio 0
	s_add_i32 s67, s67, 2
	s_add_u32 s24, s24, 0x100
	s_addc_u32 s25, s25, 0
	s_add_u32 s65, s65, 0x100
	s_addc_u32 s66, s66, 0
	s_cmp_gt_u32 s67, 29
	s_barrier

.LBB0_1056:
	s_ashr_i32 s37, s36, 31
	s_xor_b64 s[58:59], s[6:7], -1
	s_lshl_b64 s[56:57], s[36:37], 18
	s_add_u32 s56, s54, s56
	s_addc_u32 s57, s55, s57
	s_and_b64 s[60:61], s[6:7], exec
	s_cselect_b32 s9, s57, s65
	s_cselect_b32 s37, s56, s64
	s_ashr_i32 s35, s34, 31
	s_lshl_b64 s[60:61], s[34:35], 18
	s_add_u32 s60, s52, s60
	s_addc_u32 s61, s53, s61
	s_and_b64 s[68:69], s[6:7], exec
	s_cselect_b32 s35, s61, s67
	s_cselect_b32 s63, s60, s66
	s_bitcmp0_b32 s88, 0
	s_cselect_b64 vcc, -1, 0
	s_add_u32 s64, s64, 0x20080
	s_addc_u32 s65, s65, 0
	s_add_u32 s91, s66, 0x100
	v_cndmask_b32_e32 v166, v157, v156, vcc
	v_cndmask_b32_e32 v167, v159, v158, vcc
	s_addc_u32 s92, s67, 0
	s_mov_b32 s93, -2
	s_waitcnt lgkmcnt(0)
	ds_read_b128 v[150:153], v163
	ds_read_b128 v[168:171], v163 offset:1024
	ds_read_b128 v[172:175], v163 offset:2048
	ds_read_b128 v[176:179], v163 offset:3072
	s_add_u32 s33, s64, 0xfffe0080
	s_addc_u32 s68, s65, -1
	s_cmp_eq_u32 s93, 4
	s_cselect_b64 s[94:95], -1, 0
	s_and_b64 s[66:67], s[94:95], exec
	s_cselect_b32 s69, s9, s68
	s_cselect_b32 s68, s37, s33
	s_cselect_b32 s67, s35, s92
	s_cselect_b32 s66, s63, s91
	s_and_b64 vcc, s[6:7], s[94:95]
	v_cndmask_b32_e32 v132, v147, v166, vcc
	v_lshl_add_u64 v[148:149], s[64:65], 0, v[136:137]
	s_add_i32 m0, s73, 0xc000
	ds_read_b128 v[180:183], v164
	ds_read_b128 v[184:187], v164 offset:1024
	ds_read_b128 v[188:191], v164 offset:2048
	ds_read_b128 v[192:195], v164 offset:3072
	ds_read_b128 v[200:203], v164 offset:4096
	ds_read_b128 v[204:207], v164 offset:5120
	ds_read_b128 v[208:211], v164 offset:6144
	ds_read_b128 v[216:219], v164 offset:7168
	global_load_lds_dwordx4 v[148:149], off
	v_lshl_add_u64 v[148:149], s[64:65], 0, v[138:139]
	s_add_i32 m0, s73, 0xe000
	s_nop 0
	global_load_lds_dwordx4 v[148:149], off
	s_waitcnt lgkmcnt(8)
	s_barrier
	s_waitcnt lgkmcnt(0)
	v_cndmask_b32_e32 v148, v146, v167, vcc
	s_setprio 1
	s_waitcnt lgkmcnt(0)
	v_mfma_f32_16x16x32_bf16 v[124:127], v[150:153], v[180:183], 0
	v_mfma_f32_16x16x32_bf16 v[120:123], v[172:175], v[180:183], 0
	v_mfma_f32_16x16x32_bf16 v[116:119], v[150:153], v[188:191], 0
	v_mfma_f32_16x16x32_bf16 v[112:115], v[172:175], v[188:191], 0
	v_mfma_f32_16x16x32_bf16 v[108:111], v[150:153], v[200:203], 0
	v_mfma_f32_16x16x32_bf16 v[104:107], v[172:175], v[200:203], 0
	v_mfma_f32_16x16x32_bf16 v[100:103], v[150:153], v[208:211], 0
	v_mfma_f32_16x16x32_bf16 v[96:99], v[172:175], v[208:211], 0
	v_mfma_f32_16x16x32_bf16 v[124:127], v[168:171], v[184:187], v[124:127]
	v_mfma_f32_16x16x32_bf16 v[120:123], v[176:179], v[184:187], v[120:123]
	v_mfma_f32_16x16x32_bf16 v[116:119], v[168:171], v[192:195], v[116:119]
	v_mfma_f32_16x16x32_bf16 v[112:115], v[176:179], v[192:195], v[112:115]
	v_mfma_f32_16x16x32_bf16 v[108:111], v[168:171], v[204:207], v[108:111]
	v_mfma_f32_16x16x32_bf16 v[104:107], v[176:179], v[204:207], v[104:107]
	v_mfma_f32_16x16x32_bf16 v[100:103], v[168:171], v[216:219], v[100:103]
	v_mfma_f32_16x16x32_bf16 v[96:99], v[176:179], v[216:219], v[96:99]
	s_setprio 0
	s_barrier
	s_add_i32 s33, s85, s72
	s_mov_b32 m0, s33
	ds_read_b128 v[220:223], v165
	ds_read_b128 v[230:233], v165 offset:1024
	ds_read_b128 v[234:237], v165 offset:2048
	ds_read_b128 v[238:241], v165 offset:3072
	global_load_lds_dwordx4 v132, s[66:67]
	s_add_i32 m0, s33, 0x2000
	v_mov_b32_e32 v149, v133
	global_load_lds_dwordx4 v148, s[66:67]
	s_barrier
	s_waitcnt lgkmcnt(0)
	v_lshl_add_u64 v[154:155], s[66:67], 0, v[132:133]
	v_lshl_add_u64 v[196:197], s[66:67], 0, v[148:149]
	s_setprio 1
	s_waitcnt lgkmcnt(0)
	v_mfma_f32_16x16x32_bf16 v[60:63], v[220:223], v[180:183], 0
	v_mfma_f32_16x16x32_bf16 v[56:59], v[234:237], v[180:183], 0
	v_mfma_f32_16x16x32_bf16 v[52:55], v[220:223], v[188:191], 0
	v_mfma_f32_16x16x32_bf16 v[48:51], v[234:237], v[188:191], 0
	v_mfma_f32_16x16x32_bf16 v[44:47], v[220:223], v[200:203], 0
	v_mfma_f32_16x16x32_bf16 v[40:43], v[234:237], v[200:203], 0
	v_mfma_f32_16x16x32_bf16 v[36:39], v[220:223], v[208:211], 0
	v_mfma_f32_16x16x32_bf16 v[32:35], v[234:237], v[208:211], 0
	v_mfma_f32_16x16x32_bf16 v[60:63], v[230:233], v[184:187], v[60:63]
	v_mfma_f32_16x16x32_bf16 v[56:59], v[238:241], v[184:187], v[56:59]
	v_mfma_f32_16x16x32_bf16 v[52:55], v[230:233], v[192:195], v[52:55]
	v_mfma_f32_16x16x32_bf16 v[48:51], v[238:241], v[192:195], v[48:51]
	v_mfma_f32_16x16x32_bf16 v[44:47], v[230:233], v[204:207], v[44:47]
	v_mfma_f32_16x16x32_bf16 v[40:43], v[238:241], v[204:207], v[40:43]
	v_mfma_f32_16x16x32_bf16 v[36:39], v[230:233], v[216:219], v[36:39]
	v_mfma_f32_16x16x32_bf16 v[32:35], v[238:241], v[216:219], v[32:35]
	s_setprio 0
	s_mov_b32 m0, s73
	v_lshl_add_u64 v[224:225], s[68:69], 0, v[128:129]
	s_barrier
	ds_read_b128 v[180:183], v164 offset:16384
	ds_read_b128 v[184:187], v164 offset:17408
	ds_read_b128 v[188:191], v164 offset:18432
	ds_read_b128 v[192:195], v164 offset:19456
	ds_read_b128 v[200:203], v164 offset:20480
	ds_read_b128 v[204:207], v164 offset:21504
	ds_read_b128 v[208:211], v164 offset:22528
	ds_read_b128 v[216:219], v164 offset:23552
	global_load_lds_dwordx4 v[224:225], off
	v_lshl_add_u64 v[242:243], s[68:69], 0, v[130:131]
	s_mov_b32 m0, s74
	s_nop 0
	global_load_lds_dwordx4 v[242:243], off
	s_barrier
	s_waitcnt lgkmcnt(0)
	s_setprio 1
	s_waitcnt lgkmcnt(0)
	v_mfma_f32_16x16x32_bf16 v[92:95], v[150:153], v[180:183], 0
	v_mfma_f32_16x16x32_bf16 v[88:91], v[172:175], v[180:183], 0
	v_mfma_f32_16x16x32_bf16 v[84:87], v[150:153], v[188:191], 0
	v_mfma_f32_16x16x32_bf16 v[80:83], v[172:175], v[188:191], 0
	v_mfma_f32_16x16x32_bf16 v[76:79], v[150:153], v[200:203], 0
	v_mfma_f32_16x16x32_bf16 v[72:75], v[172:175], v[200:203], 0
	v_mfma_f32_16x16x32_bf16 v[68:71], v[150:153], v[208:211], 0
	v_mfma_f32_16x16x32_bf16 v[64:67], v[172:175], v[208:211], 0
	v_mfma_f32_16x16x32_bf16 v[92:95], v[168:171], v[184:187], v[92:95]
	v_mfma_f32_16x16x32_bf16 v[88:91], v[176:179], v[184:187], v[88:91]
	v_mfma_f32_16x16x32_bf16 v[84:87], v[168:171], v[192:195], v[84:87]
	v_mfma_f32_16x16x32_bf16 v[80:83], v[176:179], v[192:195], v[80:83]
	v_mfma_f32_16x16x32_bf16 v[76:79], v[168:171], v[204:207], v[76:79]
	v_mfma_f32_16x16x32_bf16 v[72:75], v[176:179], v[204:207], v[72:75]
	v_mfma_f32_16x16x32_bf16 v[68:71], v[168:171], v[216:219], v[68:71]
	v_mfma_f32_16x16x32_bf16 v[64:67], v[176:179], v[216:219], v[64:67]
	s_setprio 0
	s_barrier
	s_add_u32 s94, s66, 0x20000
	s_addc_u32 s95, s67, 0
	s_add_i32 s33, s86, s72
	s_mov_b32 m0, s33
	s_nop 0
	global_load_lds_dwordx4 v132, s[94:95]
	s_add_i32 m0, s33, 0x2000
	s_nop 0
	global_load_lds_dwordx4 v148, s[94:95]
	s_waitcnt vmcnt(6)
	s_barrier
	s_setprio 1
	v_mfma_f32_16x16x32_bf16 v[28:31], v[220:223], v[180:183], 0
	v_mfma_f32_16x16x32_bf16 v[24:27], v[234:237], v[180:183], 0
	v_mfma_f32_16x16x32_bf16 v[20:23], v[220:223], v[188:191], 0
	v_mfma_f32_16x16x32_bf16 v[16:19], v[234:237], v[188:191], 0
	v_mfma_f32_16x16x32_bf16 v[12:15], v[220:223], v[200:203], 0
	v_mfma_f32_16x16x32_bf16 v[8:11], v[234:237], v[200:203], 0
	v_mfma_f32_16x16x32_bf16 v[4:7], v[220:223], v[208:211], 0
	v_mfma_f32_16x16x32_bf16 v[0:3], v[234:237], v[208:211], 0
	v_mfma_f32_16x16x32_bf16 v[28:31], v[230:233], v[184:187], v[28:31]
	v_mfma_f32_16x16x32_bf16 v[24:27], v[238:241], v[184:187], v[24:27]
	v_mfma_f32_16x16x32_bf16 v[20:23], v[230:233], v[192:195], v[20:23]
	v_mfma_f32_16x16x32_bf16 v[16:19], v[238:241], v[192:195], v[16:19]
	v_mfma_f32_16x16x32_bf16 v[12:15], v[230:233], v[204:207], v[12:15]
	v_mfma_f32_16x16x32_bf16 v[8:11], v[238:241], v[204:207], v[8:11]
	v_mfma_f32_16x16x32_bf16 v[4:7], v[230:233], v[216:219], v[4:7]
	v_mfma_f32_16x16x32_bf16 v[0:3], v[238:241], v[216:219], v[0:3]
	s_setprio 0
	s_add_i32 s33, 0, 0x18000
	v_add_u32_e32 v149, s33, v161
	s_barrier
	ds_read_b128 v[150:153], v149
	ds_read_b128 v[168:171], v149 offset:1024
	ds_read_b128 v[172:175], v149 offset:2048
	ds_read_b128 v[176:179], v149 offset:3072
	s_add_u32 s68, s68, 0x20000
	s_addc_u32 s69, s69, 0
	s_mov_b32 m0, s75
	v_lshl_add_u64 v[220:221], s[68:69], 0, v[128:129]
	ds_read_b128 v[180:183], v164 offset:32768
	ds_read_b128 v[184:187], v164 offset:33792
	ds_read_b128 v[188:191], v164 offset:34816
	ds_read_b128 v[192:195], v164 offset:35840
	ds_read_b128 v[200:203], v164 offset:36864
	ds_read_b128 v[204:207], v164 offset:37888
	ds_read_b128 v[208:211], v164 offset:38912
	ds_read_b128 v[216:219], v164 offset:39936
	global_load_lds_dwordx4 v[220:221], off
	v_lshl_add_u64 v[220:221], s[68:69], 0, v[130:131]
	s_mov_b32 m0, s76
	s_nop 0
	global_load_lds_dwordx4 v[220:221], off
	s_waitcnt lgkmcnt(8)
	s_barrier
	s_waitcnt lgkmcnt(0)
	s_setprio 1
	s_waitcnt lgkmcnt(0)
	v_mfma_f32_16x16x32_bf16 v[124:127], v[150:153], v[180:183], v[124:127]
	v_mfma_f32_16x16x32_bf16 v[120:123], v[172:175], v[180:183], v[120:123]
	v_mfma_f32_16x16x32_bf16 v[116:119], v[150:153], v[188:191], v[116:119]
	v_mfma_f32_16x16x32_bf16 v[112:115], v[172:175], v[188:191], v[112:115]
	v_mfma_f32_16x16x32_bf16 v[108:111], v[150:153], v[200:203], v[108:111]
	v_mfma_f32_16x16x32_bf16 v[104:107], v[172:175], v[200:203], v[104:107]
	v_mfma_f32_16x16x32_bf16 v[100:103], v[150:153], v[208:211], v[100:103]
	v_mfma_f32_16x16x32_bf16 v[96:99], v[172:175], v[208:211], v[96:99]
	v_mfma_f32_16x16x32_bf16 v[124:127], v[168:171], v[184:187], v[124:127]
	v_mfma_f32_16x16x32_bf16 v[120:123], v[176:179], v[184:187], v[120:123]
	v_mfma_f32_16x16x32_bf16 v[116:119], v[168:171], v[192:195], v[116:119]
	v_mfma_f32_16x16x32_bf16 v[112:115], v[176:179], v[192:195], v[112:115]
	v_mfma_f32_16x16x32_bf16 v[108:111], v[168:171], v[204:207], v[108:111]
	v_mfma_f32_16x16x32_bf16 v[104:107], v[176:179], v[204:207], v[104:107]
	v_mfma_f32_16x16x32_bf16 v[100:103], v[168:171], v[216:219], v[100:103]
	v_mfma_f32_16x16x32_bf16 v[96:99], v[176:179], v[216:219], v[96:99]
	s_setprio 0
	s_barrier
	s_add_i32 s68, 0, 0x1c000
	s_add_i32 s33, s33, s72
	v_add_u32_e32 v149, s68, v161
	v_lshl_add_u64 v[154:155], v[154:155], 0, s[30:31]
	s_mov_b32 m0, s33
	ds_read_b128 v[220:223], v149
	ds_read_b128 v[230:233], v149 offset:1024
	ds_read_b128 v[234:237], v149 offset:2048
	ds_read_b128 v[238:241], v149 offset:3072
	global_load_lds_dwordx4 v[154:155], off
	v_lshl_add_u64 v[154:155], v[196:197], 0, s[30:31]
	s_add_i32 m0, s33, 0x2000
	s_nop 0
	global_load_lds_dwordx4 v[154:155], off
	s_barrier
	s_waitcnt lgkmcnt(0)
	s_setprio 1
	s_waitcnt lgkmcnt(0)
	v_mfma_f32_16x16x32_bf16 v[60:63], v[220:223], v[180:183], v[60:63]
	v_mfma_f32_16x16x32_bf16 v[56:59], v[234:237], v[180:183], v[56:59]
	v_mfma_f32_16x16x32_bf16 v[52:55], v[220:223], v[188:191], v[52:55]
	v_mfma_f32_16x16x32_bf16 v[48:51], v[234:237], v[188:191], v[48:51]
	v_mfma_f32_16x16x32_bf16 v[44:47], v[220:223], v[200:203], v[44:47]
	v_mfma_f32_16x16x32_bf16 v[40:43], v[234:237], v[200:203], v[40:43]
	v_mfma_f32_16x16x32_bf16 v[36:39], v[220:223], v[208:211], v[36:39]
	v_mfma_f32_16x16x32_bf16 v[32:35], v[234:237], v[208:211], v[32:35]
	v_mfma_f32_16x16x32_bf16 v[60:63], v[230:233], v[184:187], v[60:63]
	v_mfma_f32_16x16x32_bf16 v[56:59], v[238:241], v[184:187], v[56:59]
	v_mfma_f32_16x16x32_bf16 v[52:55], v[230:233], v[192:195], v[52:55]
	v_mfma_f32_16x16x32_bf16 v[48:51], v[238:241], v[192:195], v[48:51]
	v_mfma_f32_16x16x32_bf16 v[44:47], v[230:233], v[204:207], v[44:47]
	v_mfma_f32_16x16x32_bf16 v[40:43], v[238:241], v[204:207], v[40:43]
	v_mfma_f32_16x16x32_bf16 v[36:39], v[230:233], v[216:219], v[36:39]
	v_mfma_f32_16x16x32_bf16 v[32:35], v[238:241], v[216:219], v[32:35]
	s_setprio 0
	s_mov_b32 m0, s79
	v_lshl_add_u64 v[154:155], v[224:225], 0, s[30:31]
	s_barrier
	ds_read_b128 v[180:183], v164 offset:49152
	ds_read_b128 v[184:187], v164 offset:50176
	ds_read_b128 v[188:191], v164 offset:51200
	ds_read_b128 v[192:195], v164 offset:52224
	ds_read_b128 v[200:203], v164 offset:53248
	ds_read_b128 v[204:207], v164 offset:54272
	ds_read_b128 v[208:211], v164 offset:55296
	ds_read_b128 v[216:219], v164 offset:56320
	global_load_lds_dwordx4 v[154:155], off
	v_lshl_add_u64 v[154:155], v[242:243], 0, s[30:31]
	s_mov_b32 m0, s80
	s_nop 0
	global_load_lds_dwordx4 v[154:155], off
	s_barrier
	s_waitcnt lgkmcnt(0)
	s_setprio 1
	s_waitcnt lgkmcnt(0)
	v_mfma_f32_16x16x32_bf16 v[92:95], v[150:153], v[180:183], v[92:95]
	v_mfma_f32_16x16x32_bf16 v[88:91], v[172:175], v[180:183], v[88:91]
	v_mfma_f32_16x16x32_bf16 v[84:87], v[150:153], v[188:191], v[84:87]
	v_mfma_f32_16x16x32_bf16 v[80:83], v[172:175], v[188:191], v[80:83]
	v_mfma_f32_16x16x32_bf16 v[76:79], v[150:153], v[200:203], v[76:79]
	v_mfma_f32_16x16x32_bf16 v[72:75], v[172:175], v[200:203], v[72:75]
	v_mfma_f32_16x16x32_bf16 v[68:71], v[150:153], v[208:211], v[68:71]
	v_mfma_f32_16x16x32_bf16 v[64:67], v[172:175], v[208:211], v[64:67]
	v_mfma_f32_16x16x32_bf16 v[92:95], v[168:171], v[184:187], v[92:95]
	v_mfma_f32_16x16x32_bf16 v[88:91], v[176:179], v[184:187], v[88:91]
	v_mfma_f32_16x16x32_bf16 v[84:87], v[168:171], v[192:195], v[84:87]
	v_mfma_f32_16x16x32_bf16 v[80:83], v[176:179], v[192:195], v[80:83]
	v_mfma_f32_16x16x32_bf16 v[76:79], v[168:171], v[204:207], v[76:79]
	v_mfma_f32_16x16x32_bf16 v[72:75], v[176:179], v[204:207], v[72:75]
	v_mfma_f32_16x16x32_bf16 v[68:71], v[168:171], v[216:219], v[68:71]
	v_mfma_f32_16x16x32_bf16 v[64:67], v[176:179], v[216:219], v[64:67]
	s_setprio 0
	s_barrier
	s_add_u32 s66, s66, 0x20080
	s_addc_u32 s67, s67, 0
	s_add_i32 s33, s68, s72
	s_mov_b32 m0, s33
	s_nop 0
	global_load_lds_dwordx4 v132, s[66:67]
	s_add_i32 m0, s33, 0x2000
	s_nop 0
	global_load_lds_dwordx4 v148, s[66:67]
	s_waitcnt vmcnt(6)
	s_barrier
	s_setprio 1
	v_mfma_f32_16x16x32_bf16 v[28:31], v[220:223], v[180:183], v[28:31]
	v_mfma_f32_16x16x32_bf16 v[24:27], v[234:237], v[180:183], v[24:27]
	v_mfma_f32_16x16x32_bf16 v[20:23], v[220:223], v[188:191], v[20:23]
	v_mfma_f32_16x16x32_bf16 v[16:19], v[234:237], v[188:191], v[16:19]
	v_mfma_f32_16x16x32_bf16 v[12:15], v[220:223], v[200:203], v[12:15]
	v_mfma_f32_16x16x32_bf16 v[8:11], v[234:237], v[200:203], v[8:11]
	v_mfma_f32_16x16x32_bf16 v[4:7], v[220:223], v[208:211], v[4:7]
	v_mfma_f32_16x16x32_bf16 v[0:3], v[234:237], v[208:211], v[0:3]
	v_mfma_f32_16x16x32_bf16 v[28:31], v[230:233], v[184:187], v[28:31]
	v_mfma_f32_16x16x32_bf16 v[24:27], v[238:241], v[184:187], v[24:27]
	v_mfma_f32_16x16x32_bf16 v[20:23], v[230:233], v[192:195], v[20:23]
	v_mfma_f32_16x16x32_bf16 v[16:19], v[238:241], v[192:195], v[16:19]
	v_mfma_f32_16x16x32_bf16 v[12:15], v[230:233], v[204:207], v[12:15]
	v_mfma_f32_16x16x32_bf16 v[8:11], v[238:241], v[204:207], v[8:11]
	v_mfma_f32_16x16x32_bf16 v[4:7], v[230:233], v[216:219], v[4:7]
	v_mfma_f32_16x16x32_bf16 v[0:3], v[238:241], v[216:219], v[0:3]
	s_setprio 0
	s_add_i32 s93, s93, 2
	s_add_u32 s64, s64, 0x100
	s_addc_u32 s65, s65, 0
	s_add_u32 s91, s91, 0x100
	s_addc_u32 s92, s92, 0
	s_cmp_gt_u32 s93, 5
	s_barrier

.LBB0_1428:
	s_ashr_i32 s27, s26, 31
	v_cmp_lt_i64_e32 vcc, s[28:29], v[140:141]
	s_lshl_b64 s[28:29], s[26:27], 20
	s_add_u32 s28, s48, s28
	s_addc_u32 s29, s49, s29
	s_and_b64 s[30:31], vcc, exec
	s_cselect_b32 s27, s29, s35
	s_cselect_b32 s69, s28, s34
	s_ashr_i32 s25, s24, 31
	s_lshl_b64 s[30:31], s[24:25], 20
	s_add_u32 s30, s50, s30
	s_addc_u32 s31, s51, s31
	s_and_b64 s[38:39], vcc, exec
	s_cselect_b32 s25, s31, s37
	s_cselect_b32 s70, s30, s36
	s_add_u32 s34, s34, 0x80080
	s_addc_u32 s35, s35, 0
	s_add_u32 s71, s36, 0x100
	s_addc_u32 s72, s37, 0
	s_mov_b32 s73, -2
	s_waitcnt lgkmcnt(0)
	ds_read_b128 v[150:153], v147
	ds_read_b128 v[154:157], v147 offset:1024
	ds_read_b128 v[158:161], v147 offset:2048
	ds_read_b128 v[162:165], v147 offset:3072
	s_add_u32 s33, s34, 0xfff80080
	s_addc_u32 s36, s35, -1
	s_cmp_eq_u32 s73, 28
	s_cselect_b32 s39, s27, s36
	s_cselect_b32 s38, s69, s33
	s_cselect_b32 s37, s25, s72
	s_cselect_b32 s36, s70, s71
	v_lshl_add_u64 v[200:201], s[34:35], 0, v[136:137]
	s_add_i32 m0, s23, 0xc000
	ds_read_b128 v[166:169], v148
	ds_read_b128 v[170:173], v148 offset:1024
	ds_read_b128 v[174:177], v148 offset:2048
	ds_read_b128 v[178:181], v148 offset:3072
	ds_read_b128 v[182:185], v148 offset:4096
	ds_read_b128 v[186:189], v148 offset:5120
	ds_read_b128 v[190:193], v148 offset:6144
	ds_read_b128 v[194:197], v148 offset:7168
	global_load_lds_dwordx4 v[200:201], off
	v_lshl_add_u64 v[200:201], s[34:35], 0, v[138:139]
	s_add_i32 m0, s23, 0xe000
	s_nop 0
	global_load_lds_dwordx4 v[200:201], off
	s_waitcnt lgkmcnt(8)
	s_barrier
	s_waitcnt lgkmcnt(0)
	s_setprio 1
	s_waitcnt lgkmcnt(0)
	v_mfma_f32_16x16x32_bf16 v[124:127], v[150:153], v[166:169], 0
	v_mfma_f32_16x16x32_bf16 v[120:123], v[158:161], v[166:169], 0
	v_mfma_f32_16x16x32_bf16 v[116:119], v[150:153], v[174:177], 0
	v_mfma_f32_16x16x32_bf16 v[112:115], v[158:161], v[174:177], 0
	v_mfma_f32_16x16x32_bf16 v[108:111], v[150:153], v[182:185], 0
	v_mfma_f32_16x16x32_bf16 v[104:107], v[158:161], v[182:185], 0
	v_mfma_f32_16x16x32_bf16 v[100:103], v[150:153], v[190:193], 0
	v_mfma_f32_16x16x32_bf16 v[96:99], v[158:161], v[190:193], 0
	v_mfma_f32_16x16x32_bf16 v[124:127], v[154:157], v[170:173], v[124:127]
	v_mfma_f32_16x16x32_bf16 v[120:123], v[162:165], v[170:173], v[120:123]
	v_mfma_f32_16x16x32_bf16 v[116:119], v[154:157], v[178:181], v[116:119]
	v_mfma_f32_16x16x32_bf16 v[112:115], v[162:165], v[178:181], v[112:115]
	v_mfma_f32_16x16x32_bf16 v[108:111], v[154:157], v[186:189], v[108:111]
	v_mfma_f32_16x16x32_bf16 v[104:107], v[162:165], v[186:189], v[104:107]
	v_mfma_f32_16x16x32_bf16 v[100:103], v[154:157], v[194:197], v[100:103]
	v_mfma_f32_16x16x32_bf16 v[96:99], v[162:165], v[194:197], v[96:99]
	s_setprio 0
	s_barrier
	s_add_i32 s33, s62, s52
	v_lshl_add_u64 v[218:219], s[36:37], 0, v[130:131]
	s_mov_b32 m0, s33
	ds_read_b128 v[200:203], v149
	ds_read_b128 v[204:207], v149 offset:1024
	ds_read_b128 v[208:211], v149 offset:2048
	ds_read_b128 v[214:217], v149 offset:3072
	global_load_lds_dwordx4 v[218:219], off
	v_lshl_add_u64 v[220:221], s[36:37], 0, v[134:135]
	s_add_i32 m0, s33, 0x2000
	s_nop 0
	global_load_lds_dwordx4 v[220:221], off
	s_barrier
	s_waitcnt lgkmcnt(0)
	s_setprio 1
	s_waitcnt lgkmcnt(0)
	v_mfma_f32_16x16x32_bf16 v[80:83], v[200:203], v[166:169], 0
	v_mfma_f32_16x16x32_bf16 v[72:75], v[208:211], v[166:169], 0
	v_mfma_f32_16x16x32_bf16 v[68:71], v[200:203], v[174:177], 0
	v_mfma_f32_16x16x32_bf16 v[60:63], v[208:211], v[174:177], 0
	v_mfma_f32_16x16x32_bf16 v[52:55], v[200:203], v[182:185], 0
	v_mfma_f32_16x16x32_bf16 v[48:51], v[208:211], v[182:185], 0
	v_mfma_f32_16x16x32_bf16 v[36:39], v[200:203], v[190:193], 0
	v_mfma_f32_16x16x32_bf16 v[32:35], v[208:211], v[190:193], 0
	v_mfma_f32_16x16x32_bf16 v[80:83], v[204:207], v[170:173], v[80:83]
	v_mfma_f32_16x16x32_bf16 v[72:75], v[214:217], v[170:173], v[72:75]
	v_mfma_f32_16x16x32_bf16 v[68:71], v[204:207], v[178:181], v[68:71]
	v_mfma_f32_16x16x32_bf16 v[60:63], v[214:217], v[178:181], v[60:63]
	v_mfma_f32_16x16x32_bf16 v[52:55], v[204:207], v[186:189], v[52:55]
	v_mfma_f32_16x16x32_bf16 v[48:51], v[214:217], v[186:189], v[48:51]
	v_mfma_f32_16x16x32_bf16 v[36:39], v[204:207], v[194:197], v[36:39]
	v_mfma_f32_16x16x32_bf16 v[32:35], v[214:217], v[194:197], v[32:35]
	s_setprio 0
	s_mov_b32 m0, s23
	v_lshl_add_u64 v[222:223], s[38:39], 0, v[128:129]
	s_barrier
	ds_read_b128 v[166:169], v148 offset:16384
	ds_read_b128 v[170:173], v148 offset:17408
	ds_read_b128 v[174:177], v148 offset:18432
	ds_read_b128 v[178:181], v148 offset:19456
	ds_read_b128 v[182:185], v148 offset:20480
	ds_read_b128 v[186:189], v148 offset:21504
	ds_read_b128 v[190:193], v148 offset:22528
	ds_read_b128 v[194:197], v148 offset:23552
	global_load_lds_dwordx4 v[222:223], off
	v_lshl_add_u64 v[224:225], s[38:39], 0, v[132:133]
	s_mov_b32 m0, s54
	s_nop 0
	global_load_lds_dwordx4 v[224:225], off
	s_barrier
	s_waitcnt lgkmcnt(0)
	s_setprio 1
	s_waitcnt lgkmcnt(0)
	v_mfma_f32_16x16x32_bf16 v[92:95], v[150:153], v[166:169], 0
	v_mfma_f32_16x16x32_bf16 v[88:91], v[158:161], v[166:169], 0
	v_mfma_f32_16x16x32_bf16 v[84:87], v[150:153], v[174:177], 0
	v_mfma_f32_16x16x32_bf16 v[76:79], v[158:161], v[174:177], 0
	v_mfma_f32_16x16x32_bf16 v[64:67], v[150:153], v[182:185], 0
	v_mfma_f32_16x16x32_bf16 v[56:59], v[158:161], v[182:185], 0
	v_mfma_f32_16x16x32_bf16 v[44:47], v[150:153], v[190:193], 0
	v_mfma_f32_16x16x32_bf16 v[40:43], v[158:161], v[190:193], 0
	v_mfma_f32_16x16x32_bf16 v[92:95], v[154:157], v[170:173], v[92:95]
	v_mfma_f32_16x16x32_bf16 v[88:91], v[162:165], v[170:173], v[88:91]
	v_mfma_f32_16x16x32_bf16 v[84:87], v[154:157], v[178:181], v[84:87]
	v_mfma_f32_16x16x32_bf16 v[76:79], v[162:165], v[178:181], v[76:79]
	v_mfma_f32_16x16x32_bf16 v[64:67], v[154:157], v[186:189], v[64:67]
	v_mfma_f32_16x16x32_bf16 v[56:59], v[162:165], v[186:189], v[56:59]
	v_mfma_f32_16x16x32_bf16 v[44:47], v[154:157], v[194:197], v[44:47]
	v_mfma_f32_16x16x32_bf16 v[40:43], v[162:165], v[194:197], v[40:43]
	s_setprio 0
	s_barrier
	s_add_u32 s74, s36, 0x80000
	s_addc_u32 s75, s37, 0
	s_add_i32 s33, s63, s52
	v_lshl_add_u64 v[150:151], s[74:75], 0, v[130:131]
	s_mov_b32 m0, s33
	s_nop 0
	global_load_lds_dwordx4 v[150:151], off
	v_lshl_add_u64 v[150:151], s[74:75], 0, v[134:135]
	s_add_i32 m0, s33, 0x2000
	s_nop 0
	global_load_lds_dwordx4 v[150:151], off
	s_waitcnt vmcnt(6)
	s_barrier
	s_setprio 1
	v_mfma_f32_16x16x32_bf16 v[28:31], v[200:203], v[166:169], 0
	v_mfma_f32_16x16x32_bf16 v[24:27], v[208:211], v[166:169], 0
	v_mfma_f32_16x16x32_bf16 v[20:23], v[200:203], v[174:177], 0
	v_mfma_f32_16x16x32_bf16 v[16:19], v[208:211], v[174:177], 0
	v_mfma_f32_16x16x32_bf16 v[12:15], v[200:203], v[182:185], 0
	v_mfma_f32_16x16x32_bf16 v[8:11], v[208:211], v[182:185], 0
	v_mfma_f32_16x16x32_bf16 v[4:7], v[200:203], v[190:193], 0
	v_mfma_f32_16x16x32_bf16 v[0:3], v[208:211], v[190:193], 0
	v_mfma_f32_16x16x32_bf16 v[28:31], v[204:207], v[170:173], v[28:31]
	v_mfma_f32_16x16x32_bf16 v[24:27], v[214:217], v[170:173], v[24:27]
	v_mfma_f32_16x16x32_bf16 v[20:23], v[204:207], v[178:181], v[20:23]
	v_mfma_f32_16x16x32_bf16 v[16:19], v[214:217], v[178:181], v[16:19]
	v_mfma_f32_16x16x32_bf16 v[12:15], v[204:207], v[186:189], v[12:15]
	v_mfma_f32_16x16x32_bf16 v[8:11], v[214:217], v[186:189], v[8:11]
	v_mfma_f32_16x16x32_bf16 v[4:7], v[204:207], v[194:197], v[4:7]
	v_mfma_f32_16x16x32_bf16 v[0:3], v[214:217], v[194:197], v[0:3]
	s_setprio 0
	s_add_i32 s33, 0, 0x18000
	v_add_u32_e32 v162, s33, v145
	s_barrier
	ds_read_b128 v[150:153], v162
	ds_read_b128 v[154:157], v162 offset:1024
	ds_read_b128 v[158:161], v162 offset:2048
	ds_read_b128 v[162:165], v162 offset:3072
	s_add_u32 s38, s38, 0x80000
	s_addc_u32 s39, s39, 0
	s_mov_b32 m0, s55
	v_lshl_add_u64 v[200:201], s[38:39], 0, v[128:129]
	ds_read_b128 v[166:169], v148 offset:32768
	ds_read_b128 v[170:173], v148 offset:33792
	ds_read_b128 v[174:177], v148 offset:34816
	ds_read_b128 v[178:181], v148 offset:35840
	ds_read_b128 v[182:185], v148 offset:36864
	ds_read_b128 v[186:189], v148 offset:37888
	ds_read_b128 v[190:193], v148 offset:38912
	ds_read_b128 v[194:197], v148 offset:39936
	global_load_lds_dwordx4 v[200:201], off
	v_lshl_add_u64 v[200:201], s[38:39], 0, v[132:133]
	s_mov_b32 m0, s56
	s_nop 0
	global_load_lds_dwordx4 v[200:201], off
	s_waitcnt lgkmcnt(8)
	s_barrier
	s_waitcnt lgkmcnt(0)
	s_setprio 1
	s_waitcnt lgkmcnt(0)
	v_mfma_f32_16x16x32_bf16 v[124:127], v[150:153], v[166:169], v[124:127]
	v_mfma_f32_16x16x32_bf16 v[120:123], v[158:161], v[166:169], v[120:123]
	v_mfma_f32_16x16x32_bf16 v[116:119], v[150:153], v[174:177], v[116:119]
	v_mfma_f32_16x16x32_bf16 v[112:115], v[158:161], v[174:177], v[112:115]
	v_mfma_f32_16x16x32_bf16 v[108:111], v[150:153], v[182:185], v[108:111]
	v_mfma_f32_16x16x32_bf16 v[104:107], v[158:161], v[182:185], v[104:107]
	v_mfma_f32_16x16x32_bf16 v[100:103], v[150:153], v[190:193], v[100:103]
	v_mfma_f32_16x16x32_bf16 v[96:99], v[158:161], v[190:193], v[96:99]
	v_mfma_f32_16x16x32_bf16 v[124:127], v[154:157], v[170:173], v[124:127]
	v_mfma_f32_16x16x32_bf16 v[120:123], v[162:165], v[170:173], v[120:123]
	v_mfma_f32_16x16x32_bf16 v[116:119], v[154:157], v[178:181], v[116:119]
	v_mfma_f32_16x16x32_bf16 v[112:115], v[162:165], v[178:181], v[112:115]
	v_mfma_f32_16x16x32_bf16 v[108:111], v[154:157], v[186:189], v[108:111]
	v_mfma_f32_16x16x32_bf16 v[104:107], v[162:165], v[186:189], v[104:107]
	v_mfma_f32_16x16x32_bf16 v[100:103], v[154:157], v[194:197], v[100:103]
	v_mfma_f32_16x16x32_bf16 v[96:99], v[162:165], v[194:197], v[96:99]
	s_setprio 0
	s_barrier
	s_add_i32 s38, 0, 0x1c000
	s_add_i32 s33, s33, s52
	v_add_u32_e32 v199, s38, v145
	v_lshl_add_u64 v[218:219], v[218:219], 0, s[14:15]
	s_mov_b32 m0, s33
	ds_read_b128 v[200:203], v199
	ds_read_b128 v[204:207], v199 offset:1024
	ds_read_b128 v[208:211], v199 offset:2048
	ds_read_b128 v[214:217], v199 offset:3072
	global_load_lds_dwordx4 v[218:219], off
	v_lshl_add_u64 v[218:219], v[220:221], 0, s[14:15]
	s_add_i32 m0, s33, 0x2000
	s_nop 0
	global_load_lds_dwordx4 v[218:219], off
	s_barrier
	s_waitcnt lgkmcnt(0)
	s_setprio 1
	s_waitcnt lgkmcnt(0)
	v_mfma_f32_16x16x32_bf16 v[80:83], v[200:203], v[166:169], v[80:83]
	v_mfma_f32_16x16x32_bf16 v[72:75], v[208:211], v[166:169], v[72:75]
	v_mfma_f32_16x16x32_bf16 v[68:71], v[200:203], v[174:177], v[68:71]
	v_mfma_f32_16x16x32_bf16 v[60:63], v[208:211], v[174:177], v[60:63]
	v_mfma_f32_16x16x32_bf16 v[52:55], v[200:203], v[182:185], v[52:55]
	v_mfma_f32_16x16x32_bf16 v[48:51], v[208:211], v[182:185], v[48:51]
	v_mfma_f32_16x16x32_bf16 v[36:39], v[200:203], v[190:193], v[36:39]
	v_mfma_f32_16x16x32_bf16 v[32:35], v[208:211], v[190:193], v[32:35]
	v_mfma_f32_16x16x32_bf16 v[80:83], v[204:207], v[170:173], v[80:83]
	v_mfma_f32_16x16x32_bf16 v[72:75], v[214:217], v[170:173], v[72:75]
	v_mfma_f32_16x16x32_bf16 v[68:71], v[204:207], v[178:181], v[68:71]
	v_mfma_f32_16x16x32_bf16 v[60:63], v[214:217], v[178:181], v[60:63]
	v_mfma_f32_16x16x32_bf16 v[52:55], v[204:207], v[186:189], v[52:55]
	v_mfma_f32_16x16x32_bf16 v[48:51], v[214:217], v[186:189], v[48:51]
	v_mfma_f32_16x16x32_bf16 v[36:39], v[204:207], v[194:197], v[36:39]
	v_mfma_f32_16x16x32_bf16 v[32:35], v[214:217], v[194:197], v[32:35]
	s_setprio 0
	s_mov_b32 m0, s59
	v_lshl_add_u64 v[218:219], v[222:223], 0, s[14:15]
	s_barrier
	ds_read_b128 v[166:169], v148 offset:49152
	ds_read_b128 v[170:173], v148 offset:50176
	ds_read_b128 v[174:177], v148 offset:51200
	ds_read_b128 v[178:181], v148 offset:52224
	ds_read_b128 v[182:185], v148 offset:53248
	ds_read_b128 v[186:189], v148 offset:54272
	ds_read_b128 v[190:193], v148 offset:55296
	ds_read_b128 v[194:197], v148 offset:56320
	global_load_lds_dwordx4 v[218:219], off
	v_lshl_add_u64 v[218:219], v[224:225], 0, s[14:15]
	s_mov_b32 m0, s60
	s_nop 0
	global_load_lds_dwordx4 v[218:219], off
	s_barrier
	s_waitcnt lgkmcnt(0)
	s_setprio 1
	s_waitcnt lgkmcnt(0)
	v_mfma_f32_16x16x32_bf16 v[92:95], v[150:153], v[166:169], v[92:95]
	v_mfma_f32_16x16x32_bf16 v[88:91], v[158:161], v[166:169], v[88:91]
	v_mfma_f32_16x16x32_bf16 v[84:87], v[150:153], v[174:177], v[84:87]
	v_mfma_f32_16x16x32_bf16 v[76:79], v[158:161], v[174:177], v[76:79]
	v_mfma_f32_16x16x32_bf16 v[64:67], v[150:153], v[182:185], v[64:67]
	v_mfma_f32_16x16x32_bf16 v[56:59], v[158:161], v[182:185], v[56:59]
	v_mfma_f32_16x16x32_bf16 v[44:47], v[150:153], v[190:193], v[44:47]
	v_mfma_f32_16x16x32_bf16 v[40:43], v[158:161], v[190:193], v[40:43]
	v_mfma_f32_16x16x32_bf16 v[92:95], v[154:157], v[170:173], v[92:95]
	v_mfma_f32_16x16x32_bf16 v[88:91], v[162:165], v[170:173], v[88:91]
	v_mfma_f32_16x16x32_bf16 v[84:87], v[154:157], v[178:181], v[84:87]
	v_mfma_f32_16x16x32_bf16 v[76:79], v[162:165], v[178:181], v[76:79]
	v_mfma_f32_16x16x32_bf16 v[64:67], v[154:157], v[186:189], v[64:67]
	v_mfma_f32_16x16x32_bf16 v[56:59], v[162:165], v[186:189], v[56:59]
	v_mfma_f32_16x16x32_bf16 v[44:47], v[154:157], v[194:197], v[44:47]
	v_mfma_f32_16x16x32_bf16 v[40:43], v[162:165], v[194:197], v[40:43]
	s_setprio 0
	s_barrier
	s_add_u32 s36, s36, 0x80080
	s_addc_u32 s37, s37, 0
	s_add_i32 s33, s38, s52
	v_lshl_add_u64 v[150:151], s[36:37], 0, v[130:131]
	s_mov_b32 m0, s33
	s_nop 0
	global_load_lds_dwordx4 v[150:151], off
	v_lshl_add_u64 v[150:151], s[36:37], 0, v[134:135]
	s_add_i32 m0, s33, 0x2000
	s_nop 0
	global_load_lds_dwordx4 v[150:151], off
	s_waitcnt vmcnt(6)
	s_barrier
	s_setprio 1
	v_mfma_f32_16x16x32_bf16 v[28:31], v[200:203], v[166:169], v[28:31]
	v_mfma_f32_16x16x32_bf16 v[24:27], v[208:211], v[166:169], v[24:27]
	v_mfma_f32_16x16x32_bf16 v[20:23], v[200:203], v[174:177], v[20:23]
	v_mfma_f32_16x16x32_bf16 v[16:19], v[208:211], v[174:177], v[16:19]
	v_mfma_f32_16x16x32_bf16 v[12:15], v[200:203], v[182:185], v[12:15]
	v_mfma_f32_16x16x32_bf16 v[8:11], v[208:211], v[182:185], v[8:11]
	v_mfma_f32_16x16x32_bf16 v[4:7], v[200:203], v[190:193], v[4:7]
	v_mfma_f32_16x16x32_bf16 v[0:3], v[208:211], v[190:193], v[0:3]
	v_mfma_f32_16x16x32_bf16 v[28:31], v[204:207], v[170:173], v[28:31]
	v_mfma_f32_16x16x32_bf16 v[24:27], v[214:217], v[170:173], v[24:27]
	v_mfma_f32_16x16x32_bf16 v[20:23], v[204:207], v[178:181], v[20:23]
	v_mfma_f32_16x16x32_bf16 v[16:19], v[214:217], v[178:181], v[16:19]
	v_mfma_f32_16x16x32_bf16 v[12:15], v[204:207], v[186:189], v[12:15]
	v_mfma_f32_16x16x32_bf16 v[8:11], v[214:217], v[186:189], v[8:11]
	v_mfma_f32_16x16x32_bf16 v[4:7], v[204:207], v[194:197], v[4:7]
	v_mfma_f32_16x16x32_bf16 v[0:3], v[214:217], v[194:197], v[0:3]
	s_setprio 0
	s_add_i32 s73, s73, 2
	s_add_u32 s34, s34, 0x100
	s_addc_u32 s35, s35, 0
	s_add_u32 s71, s71, 0x100
	s_addc_u32 s72, s72, 0
	s_cmp_gt_u32 s73, 29
	s_barrier
